# gates GEMM re-split 192 early + 832 on 208 WGs (4 rounds), GLA chain compute hand-pipelined, RG-LRU carry scan with all loads in flight (moved to GLA WGs), counted vmcnt in chain staging
# speedup vs baseline: 1.0090x; 1.0090x over previous
.LBB0_522:
	s_or_b64 exec, exec, s[2:3]
	s_add_u32 s2, s82, 0xe000000
	s_addc_u32 s3, s83, 0
	s_add_u32 s54, s82, 0x19500000
	v_writelane_b32 v252, s2, 34
	s_addc_u32 s55, s83, 0
	v_mbcnt_hi_u32_b32 v239, -1, v1
	v_writelane_b32 v252, s3, 35
	s_add_u32 s2, s82, 0x1b500000
	s_addc_u32 s3, s83, 0
	v_writelane_b32 v252, s2, 36
	v_and_b32_e32 v0, 64, v239
	v_mov_b32_e32 v236, 0x358637bd
	v_writelane_b32 v252, s3, 37
	s_add_u32 s2, s82, 0x1f500000
	s_addc_u32 s3, s83, 0
	v_writelane_b32 v252, s2, 38
	v_mov_b32_e32 v17, 0
	v_mov_b32_e32 v237, 1
	v_writelane_b32 v252, s3, 39
	s_add_u32 s2, s82, 0x1f640000
	v_writelane_b32 v252, s2, 40
	s_addc_u32 s2, s83, 0
	v_writelane_b32 v252, s2, 41
	s_add_u32 s2, s82, 0x1f7c0000
	v_writelane_b32 v252, s2, 42
	s_addc_u32 s2, s83, 0
	v_writelane_b32 v252, s2, 43
	s_add_u32 s2, s82, 0x1f880000
	v_writelane_b32 v252, s2, 44
	s_addc_u32 s2, s83, 0
	v_writelane_b32 v252, s2, 45
	s_add_u32 s2, s82, 0x1f980000
	v_writelane_b32 v252, s2, 46
	s_addc_u32 s2, s83, 0
	v_writelane_b32 v252, s2, 47
	s_add_u32 s2, s82, 0x16000000
	v_writelane_b32 v252, s2, 48
	s_addc_u32 s2, s83, 0
	v_writelane_b32 v252, s2, 49
	s_add_u32 s2, s82, 0x17900000
	v_writelane_b32 v252, s2, 50
	s_addc_u32 s2, s83, 0
	v_writelane_b32 v252, s2, 51
	s_add_u32 s2, s82, 0x18900000
	v_writelane_b32 v252, s2, 52
	s_addc_u32 s2, s83, 0
	v_writelane_b32 v252, s2, 53
	s_add_u32 s2, s82, 0x19100000
	v_writelane_b32 v252, s2, 54
	s_addc_u32 s2, s83, 0
	v_writelane_b32 v252, s2, 55
	s_mul_i32 s2, s63, s62
	s_lshl_b32 s16, s62, 5
	s_mul_i32 s2, s2, s30
	v_writelane_b32 v252, s2, 56
	s_add_u32 s2, s82, 0x1fa01200
	s_addc_u32 s3, s83, 0
	v_writelane_b32 v252, s2, 57
	s_movk_i32 s63, 0x90
	v_mov_b32_e32 v238, 0x260
	v_writelane_b32 v252, s3, 58
	s_add_u32 s2, s82, 0x1fa01400
	s_addc_u32 s3, s83, 0
	v_writelane_b32 v252, s2, 59
	v_add_u32_e32 v240, 64, v0
	v_xor_b32_e32 v246, 32, v239
	v_writelane_b32 v252, s3, 60
	s_add_u32 s2, s82, 0x1fa01500
	s_addc_u32 s3, s83, 0
	v_writelane_b32 v252, s2, 61
	v_xor_b32_e32 v245, 16, v239
	v_xor_b32_e32 v244, 8, v239
	v_writelane_b32 v252, s3, 62
	s_add_u32 s2, s82, 0x1fa01600
	s_addc_u32 s3, s83, 0
	v_writelane_b32 v252, s2, 63
	v_xor_b32_e32 v243, 4, v239
	v_xor_b32_e32 v242, 2, v239
	v_writelane_b32 v253, s3, 0
	s_add_u32 s2, s82, 0x1fa01700
	s_addc_u32 s3, s83, 0
	v_writelane_b32 v253, s2, 1
	v_xor_b32_e32 v241, 1, v239
	v_mov_b64_e32 v[234:235], 0x63f
	v_writelane_b32 v253, s3, 2
	s_add_u32 s2, s82, 0x1fa01800
	s_addc_u32 s3, s83, 0
	v_writelane_b32 v253, s2, 3
	v_mov_b64_e32 v[184:185], 0x700
	v_mov_b32_e32 v247, 0x300
	v_writelane_b32 v253, s3, 4
	s_add_u32 s2, s82, 0x1fa01900
	s_addc_u32 s3, s83, 0
	v_writelane_b32 v253, s2, 5
	v_mov_b32_e32 v248, 0x41b17218
	v_mov_b32_e32 v249, 0x600
	v_writelane_b32 v253, s3, 6
	s_add_u32 s2, s82, 0x1fa01a00
	s_addc_u32 s3, s83, 0
	v_writelane_b32 v253, s2, 7
	v_mov_b32_e32 v182, 0x3b000000
	v_mov_b64_e32 v[228:229], 0x33f
	v_writelane_b32 v253, s3, 8
	s_add_u32 s2, s82, 0x1fa01b00
	s_addc_u32 s3, s83, 0
	v_writelane_b32 v253, s2, 9
	v_mov_b64_e32 v[186:187], 0xff
	s_mov_b32 s27, 0x800000
	v_writelane_b32 v253, s3, 10
	s_add_u32 s2, s82, 0x1fa01c00
	s_addc_u32 s3, s83, 0
	v_writelane_b32 v253, s2, 11
	s_movk_i32 s77, 0x2000
	s_movk_i32 s95, 0x6000
	v_writelane_b32 v253, s3, 12
	s_add_u32 s2, s82, 0x1fa01d00
	s_addc_u32 s3, s83, 0
	v_writelane_b32 v253, s2, 13
	s_mov_b32 s59, 0x18000
	s_mov_b32 s61, 0xa000
	v_writelane_b32 v253, s3, 14
	s_add_u32 s2, s82, 0x1fa01e00
	s_addc_u32 s3, s83, 0
	v_writelane_b32 v253, s2, 15
	s_mov_b32 s65, 0x1c000
	s_mov_b32 s87, 0xbfb8aa3b
	v_writelane_b32 v253, s3, 16
	s_add_u32 s2, s82, 0x1fa01f00
	s_addc_u32 s3, s83, 0
	v_writelane_b32 v253, s2, 17
	s_mov_b32 s31, 0x437f0000
	s_movk_i32 s60, 0x1c00
	v_writelane_b32 v253, s3, 18
	s_add_u32 s2, s82, 0x1fa02000
	s_addc_u32 s3, s83, 0
	v_writelane_b32 v253, s2, 19
	s_movk_i32 s57, 0x3000
	s_movk_i32 s76, 0x7000
	v_writelane_b32 v253, s3, 20
	s_add_u32 s2, s82, 0x1fa02100
	s_addc_u32 s3, s83, 0
	v_writelane_b32 v253, s2, 21
	s_mov_b32 s91, 0x11000
	s_mov_b32 s58, 0x31000
	v_writelane_b32 v253, s3, 22
	s_add_u32 s2, s82, 0x1fa02200
	s_addc_u32 s3, s83, 0
	v_writelane_b32 v253, s2, 23
	s_mov_b32 s64, 0x34000
	s_mov_b32 s29, 0x3f317217
	v_writelane_b32 v253, s3, 24
	s_add_u32 s2, s82, 0x1fa02300
	s_addc_u32 s3, s83, 0
	v_writelane_b32 v253, s2, 25
	s_cmp_eq_u32 s7, 15
	s_mov_b32 s93, 0x7f800000
	v_writelane_b32 v253, s3, 26
	s_cselect_b64 s[2:3], -1, 0
	v_writelane_b32 v253, s2, 27
	s_cmp_eq_u32 s7, 14
	s_mov_b32 s94, 0x3e2aaaab
	v_writelane_b32 v253, s3, 28
	s_cselect_b64 s[2:3], -1, 0
	v_writelane_b32 v253, s2, 29
	s_cmp_eq_u32 s7, 13
	s_mov_b32 s75, 0xf800000
	v_writelane_b32 v253, s3, 30
	s_cselect_b64 s[2:3], -1, 0
	v_writelane_b32 v253, s2, 31
	s_cmp_eq_u32 s7, 12
	s_mov_b32 s85, 0x3e6d3388
	v_writelane_b32 v253, s3, 32
	s_cselect_b64 s[2:3], -1, 0
	v_writelane_b32 v253, s2, 33
	s_cmp_eq_u32 s7, 11
	s_mov_b64 s[36:37], 0xe0000
	v_writelane_b32 v253, s3, 34
	s_cselect_b64 s[2:3], -1, 0
	v_writelane_b32 v253, s2, 35
	s_cmp_eq_u32 s7, 10
	s_mov_b32 s92, 0x3db504f3
	v_writelane_b32 v253, s3, 36
	s_cselect_b64 s[2:3], -1, 0
	v_writelane_b32 v253, s2, 37
	s_cmp_eq_u32 s7, 9
	s_mov_b64 s[66:67], 0x2a00
	v_writelane_b32 v253, s3, 38
	s_cselect_b64 s[2:3], -1, 0
	v_writelane_b32 v253, s2, 39
	s_cmp_eq_u32 s7, 8
	s_mov_b32 s74, 0x3f07dc22
	v_writelane_b32 v253, s3, 40
	s_cselect_b64 s[2:3], -1, 0
	v_writelane_b32 v253, s2, 41
	s_cmp_eq_u32 s7, 7
	s_mov_b32 s84, 0x3f35f0e3
	v_writelane_b32 v253, s3, 42
	s_cselect_b64 s[2:3], -1, 0
	v_writelane_b32 v253, s2, 43
	s_cmp_eq_u32 s7, 6
	s_mov_b32 s86, 0xbe11a98e
	v_writelane_b32 v253, s3, 44
	s_cselect_b64 s[2:3], -1, 0
	v_writelane_b32 v253, s2, 45
	s_cmp_eq_u32 s7, 5
	s_mov_b32 s24, 0x3e027906
	v_writelane_b32 v253, s3, 46
	s_cselect_b64 s[2:3], -1, 0
	v_writelane_b32 v253, s2, 47
	s_cmp_eq_u32 s7, 4
	s_mov_b32 s26, 0x3b000000
	v_writelane_b32 v253, s3, 48
	s_cselect_b64 s[2:3], -1, 0
	v_writelane_b32 v253, s2, 49
	s_cmp_eq_u32 s7, 3
	s_mov_b32 s28, 0x358637bd
	v_writelane_b32 v253, s3, 50
	s_cselect_b64 s[2:3], -1, 0
	v_writelane_b32 v253, s2, 51
	s_cmp_eq_u32 s7, 2
	s_mov_b32 s30, 0x3b808081
	v_writelane_b32 v253, s3, 52
	s_cselect_b64 s[2:3], -1, 0
	v_writelane_b32 v253, s2, 53
	s_cmp_eq_u32 s7, 1
	s_nop 0
	v_writelane_b32 v253, s3, 54
	s_cselect_b64 s[2:3], -1, 0
	v_writelane_b32 v253, s2, 55
	s_cmp_eq_u32 s7, 0
	s_nop 0
	v_writelane_b32 v253, s3, 56
	s_cselect_b64 s[2:3], -1, 0
	v_writelane_b32 v253, s2, 57
	s_nop 1
	v_writelane_b32 v253, s3, 58
	s_lshl_b32 s2, s6, 2
	s_add_u32 s0, s0, s2
	s_addc_u32 s1, s1, 0
	s_add_u32 s2, s0, 0x1400
	s_addc_u32 s3, s1, 0
	v_writelane_b32 v253, s2, 59
	s_add_u32 s0, s0, 0x2400
	s_addc_u32 s1, s1, 0
	v_writelane_b32 v253, s3, 60
	v_writelane_b32 v253, s0, 61
	s_nop 1
	v_writelane_b32 v253, s1, 62
	s_add_u32 s0, s82, 0x1fa04400
	s_addc_u32 s1, s83, 0
	v_writelane_b32 v253, s0, 63
	s_nop 1
	v_writelane_b32 v254, s1, 0
	s_add_u32 s0, s82, 0x1fa04500
	s_addc_u32 s1, s83, 0
	v_writelane_b32 v254, s0, 1
	s_add_u32 s34, s82, 0x1f510000
	s_addc_u32 s35, s83, 0
	v_writelane_b32 v254, s1, 2
	s_ashr_i32 s0, s62, 31
	s_lshl_b32 s18, s62, 9
	v_writelane_b32 v254, s0, 3
	s_add_u32 s0, s82, 0x1fa00000
	v_writelane_b32 v254, s0, 4
	s_addc_u32 s0, s83, 0
	v_writelane_b32 v254, s0, 5
	s_sub_i32 s0, s62, 48
	v_writelane_b32 v254, s0, 6
	s_ashr_i32 s0, s0, 31
	v_writelane_b32 v254, s0, 7
	s_add_u32 s0, s82, 0x1000
	s_addc_u32 s1, s83, 0
	v_writelane_b32 v254, s0, 8
	s_ashr_i32 s17, s16, 31
	s_nop 0
	v_writelane_b32 v254, s1, 9
	s_lshl_b64 s[0:1], s[16:17], 2
	v_writelane_b32 v254, s0, 10
	s_nop 1
	v_writelane_b32 v254, s1, 11
	v_readlane_b32 s0, v252, 1
	v_readlane_b32 s1, v252, 2
	s_add_u32 s0, s0, 0x3c00
	v_writelane_b32 v254, s0, 12
	s_addc_u32 s0, s1, 0
	v_writelane_b32 v254, s0, 13
	s_lshl_b64 s[0:1], s[16:17], 12
	v_writelane_b32 v254, s0, 14
	s_ashr_i32 s19, s18, 31
	v_readlane_b32 s4, v252, 5
	v_writelane_b32 v254, s1, 15
	s_mov_b32 s0, s16
	v_writelane_b32 v254, s0, 16
	v_readlane_b32 s5, v252, 6
	s_mov_b64 s[4:5], 0
	v_writelane_b32 v254, s1, 17
	s_lshl_b64 s[0:1], s[16:17], 11
	v_writelane_b32 v254, s0, 18
	v_readlane_b32 s3, v252, 4
	v_readlane_b32 s14, v252, 15
	v_writelane_b32 v254, s1, 19
	s_lshl_b64 s[0:1], s[18:19], 4
	v_writelane_b32 v254, s0, 20
	v_readlane_b32 s15, v252, 16
	s_mov_b32 s3, 0xbca3d70a
	v_writelane_b32 v254, s1, 21
	s_mov_b32 s0, s18
	v_writelane_b32 v254, s0, 22
	s_mov_b64 s[14:15], 0x80
	v_readlane_b32 s2, v252, 3
	v_writelane_b32 v254, s1, 23
	s_lshl_b64 s[0:1], s[18:19], 2
	v_writelane_b32 v254, s0, 24
	s_mov_b32 s19, 0x5040100
	s_mov_b32 s18, 0x45800000
	v_writelane_b32 v254, s1, 25
	s_add_u32 s0, s82, 0x1840
	s_addc_u32 s1, s83, 0
	v_writelane_b32 v254, s0, 26
	v_readlane_b32 s6, v252, 7
	v_readlane_b32 s7, v252, 8
	v_writelane_b32 v254, s1, 27
	s_lshl_b32 s0, s62, 6
	v_writelane_b32 v254, s0, 28
	s_lshl_b32 s0, s62, 1
	v_writelane_b32 v254, s0, 29
	s_add_i32 s0, 0, 0x23fe0
	v_writelane_b32 v254, s0, 30
	s_add_i32 s0, 0, 0x23fe4
	v_writelane_b32 v254, s0, 31
	s_add_i32 s0, 0, 0x23ff0
	v_writelane_b32 v254, s0, 32
	s_add_i32 s0, 0, 0x1c400
	v_writelane_b32 v254, s0, 33
	s_add_i32 s0, 0, 0x1cc00
	v_writelane_b32 v254, s0, 34
	s_add_i32 s0, 0, 0x14400
	v_writelane_b32 v254, s0, 35
	s_add_i32 s0, 0, 0xc400
	v_writelane_b32 v254, s0, 36
	s_add_i32 s0, 0, 0x1b400
	v_writelane_b32 v254, s0, 37
	s_add_i32 s0, 0, 0x1fc00
	v_writelane_b32 v254, s0, 38
	s_add_i32 s0, 0, 0x14800
	v_writelane_b32 v254, s0, 39
	s_add_i32 s0, 0, 0x10400
	v_writelane_b32 v254, s0, 40
	s_add_i32 s0, 0, 0x16c00
	v_writelane_b32 v254, s0, 41
	s_add_i32 s0, 0, 0x1fe00
	v_writelane_b32 v254, s0, 42
	s_add_i32 s0, 0, 0x1fd00
	v_writelane_b32 v254, s0, 43
	v_writelane_b32 v254, s4, 44
	s_mov_b64 s[0:1], -1
	v_readlane_b32 s8, v252, 9
	v_writelane_b32 v254, s5, 45
	v_writelane_b32 v254, s34, 46
	s_mov_b32 s4, s97
	v_readlane_b32 s9, v252, 10
	v_writelane_b32 v254, s35, 47
	v_writelane_b32 v254, s62, 48
	v_readlane_b32 s10, v252, 11
	v_readlane_b32 s11, v252, 12
	v_writelane_b32 v254, s63, 49
	v_writelane_b32 v254, s88, 50
	v_readlane_b32 s12, v252, 13
	v_readlane_b32 s13, v252, 14
	v_writelane_b32 v254, s89, 51
	v_writelane_b32 v254, s54, 52
	s_nop 1
	v_writelane_b32 v254, s55, 53
	s_branch .LBB0_524

.LBB0_649:
	s_mul_i32 s0, s40, 0xc80000
	v_readlane_b32 s1, v252, 48
	s_mov_b32 s41, s97
	s_add_u32 s0, s1, s0
	v_readlane_b32 s1, v252, 49
	s_addc_u32 s1, s1, 0
	s_lshl_b64 s[6:7], s[40:41], 23
	v_readlane_b32 s2, v252, 50
	s_add_u32 s6, s2, s6
	v_readlane_b32 s2, v252, 51
	s_addc_u32 s7, s2, s7
	v_mov_b32_e32 v0, v232
	v_writelane_b32 v254, s6, 63
	s_cmpk_gt_i32 s42, 0x63f
	v_readfirstlane_b32 s2, v0
	v_writelane_b32 v255, s7, 0
	s_cbranch_scc0 .LBB0_654
	s_mov_b64 s[6:7], 0
	s_cmpk_lt_u32 s42, 0x700
	s_mov_b64 s[8:9], 0
	s_mov_b32 s35, 0x1f000
	s_cbranch_scc0 .LBB0_652
	s_lshl_b32 s8, s42, 3
	s_nop 0
	s_and_b32 s8, s8, 56
	s_bfe_u32 s9, s42, 0x30003
	s_or_b32 s34, s8, s9
	s_mov_b64 s[8:9], -1

.LBB0_655:
	v_readlane_b32 s6, v254, 63
	s_sub_i32 s22, s42, 0x300
	s_lshr_b32 s22, s22, 6
	s_mov_b32 s51, 1
	v_readlane_b32 s7, v255, 0

.LBB0_661:
	s_add_i32 s49, s49, 1
	v_readlane_b32 s11, v254, 3
	s_mul_i32 s11, s49, s11
	s_mul_hi_u32 s12, s49, s62
	s_add_i32 s11, s12, s11
	s_mul_i32 s12, s49, s62
	v_readlane_b32 s13, v255, 1
	s_add_u32 s12, s12, s13
	s_addc_u32 s13, s11, s48
	v_cmp_gt_i64_e32 vcc, s[12:13], v[234:235]
	s_cbranch_vccz .LBB0_664
	v_cmp_lt_u64_e32 vcc, s[12:13], v[184:185]
	s_mov_b64 s[44:45], 0
	s_mov_b64 s[42:43], 0
	s_cbranch_vccz .LBB0_665
	s_nop 0
	s_lshl_b32 s11, s12, 3
	s_and_b32 s11, s11, 56
	s_bfe_u32 s10, s12, 0x30003
	s_or_b32 s16, s11, s10
	s_mov_b64 s[42:43], -1
	s_mov_b32 s50, 1
	s_sub_i32 s10, s12, 0x300
	s_lshr_b32 s10, s10, 6
	s_branch .LBB0_665

.LBB0_947:
	s_or_b64 exec, exec, s[0:1]
	s_cmp_gt_i32 s50, 31
	s_mov_b64 s[0:1], -1
	s_waitcnt lgkmcnt(0)
	s_barrier
	s_cbranch_scc0 .LBB0_1001
	s_cmp_gt_u32 s50, 47
	s_cbranch_scc0 .LBB0_971
	s_sub_i32 s2, s50, 48
	v_mov_b32_e32 v14, v232
	s_cmpk_gt_u32 s2, 0x33f
	v_readfirstlane_b32 s34, v14
	s_cbranch_scc1 .LBB0_967
	v_lshlrev_b32_e32 v0, 4, v14
	v_add_u32_e32 v1, 0x2000, v0
	v_ashrrev_i32_e32 v2, 31, v1
	v_lshrrev_b32_e32 v2, 22, v2
	v_add_u32_e32 v2, v1, v2
	v_ashrrev_i32_e32 v8, 10, v2
	v_mul_i32_i24_e32 v2, 0x400, v8
	v_sub_u32_e32 v1, v1, v2
	v_lshrrev_b32_e32 v2, 4, v1
	v_bitop3_b32 v1, v2, v1, 32 bitop3:0x6c
	v_ashrrev_i32_e32 v2, 31, v1
	v_lshrrev_b32_e32 v2, 26, v2
	v_add_u32_e32 v2, v1, v2
	v_lshlrev_b32_e32 v3, 3, v8
	v_ashrrev_i32_e32 v9, 6, v2
	v_and_b32_e32 v3, -16, v3
	v_add_u32_e32 v3, v9, v3
	v_and_b32_e32 v4, 3, v9
	s_mov_b32 s4, 0x1fffe0
	v_lshrrev_b32_e32 v5, 2, v3
	v_lshlrev_b32_e32 v6, 1, v3
	v_and_b32_e32 v2, 0xc0, v2
	v_and_or_b32 v4, v3, s4, v4
	v_and_b32_e32 v5, 4, v5
	v_and_b32_e32 v6, 24, v6
	v_sub_u32_e32 v1, v1, v2
	v_or3_b32 v4, v4, v5, v6
	v_lshlrev_b32_e32 v5, 5, v8
	v_ashrrev_i16_sdwa v1, v237, sext(v1) dst_sel:DWORD dst_unused:UNUSED_PAD src0_sel:DWORD src1_sel:BYTE_0
	v_and_b32_e32 v5, 32, v5
	v_bfe_i32 v10, v1, 0, 16
	v_add_lshl_u32 v1, v5, v10, 1
	v_lshl_add_u32 v130, v4, 11, v1
	v_lshl_add_u32 v132, v3, 11, v1
	v_bfe_i32 v1, v14, 27, 1
	v_lshrrev_b32_e32 v1, 22, v1
	v_add_u32_e32 v1, v0, v1
	v_and_b32_e32 v1, 0xfffffc00, v1
	v_sub_u32_e32 v0, v0, v1
	v_lshrrev_b32_e32 v1, 4, v0
	v_bitop3_b32 v1, v1, v0, 32 bitop3:0x6c
	v_ashrrev_i32_e32 v0, 31, v0
	v_lshrrev_b32_e32 v0, 26, v0
	v_add_u32_e32 v0, v1, v0
	v_ashrrev_i32_e32 v11, 6, v0
	v_ashrrev_i32_e32 v0, 31, v14
	v_lshrrev_b32_e32 v0, 26, v0
	v_add_u32_e32 v0, v14, v0
	v_ashrrev_i32_e32 v12, 6, v0
	v_lshlrev_b32_e32 v0, 3, v12
	v_and_b32_e32 v0, -16, v0
	v_add_u32_e32 v0, v11, v0
	v_and_b32_e32 v2, 3, v11
	v_and_or_b32 v2, v0, s4, v2
	s_lshl_b32 s4, s50, 3
	v_lshrrev_b32_e32 v3, 2, v0
	v_lshlrev_b32_e32 v4, 1, v0
	s_and_b32 s4, s4, 56
	s_bfe_u32 s5, s2, 0x30003
	s_ashr_i32 s0, s34, 6
	v_and_b32_e32 v3, 4, v3
	v_and_b32_e32 v4, 24, v4
	s_or_b32 s21, s4, s5
	s_ashr_i32 s1, s34, 8
	s_lshl_b32 s35, s0, 10
	v_or3_b32 v2, v2, v3, v4
	v_mul_i32_i24_e32 v4, 64, v11
	s_bfe_u32 s4, s2, 0x50006
	s_lshl_b32 s5, s21, 19
	v_sub_u32_e32 v1, v1, v4
	s_add_u32 s12, s54, s5
	v_lshlrev_b32_e32 v3, 5, v12
	v_ashrrev_i16_sdwa v1, v237, sext(v1) dst_sel:DWORD dst_unused:UNUSED_PAD src0_sel:DWORD src1_sel:BYTE_0
	s_addc_u32 s13, s55, 0
	s_lshl_b32 s5, s4, 19
	v_readlane_b32 s6, v254, 63
	v_and_b32_e32 v3, 32, v3
	v_bfe_i32 v13, v1, 0, 16
	v_readlane_b32 s7, v255, 0
	s_add_u32 s16, s6, s5
	v_add_lshl_u32 v1, v3, v13, 1
	s_addc_u32 s17, s7, 0
	s_add_i32 s38, s35, 0
	v_lshl_add_u32 v16, v2, 11, v1
	s_add_i32 m0, s38, 0x10000
	v_lshl_add_u32 v134, v0, 11, v1
	global_load_lds_dwordx4 v16, s[16:17]
	s_add_i32 m0, s38, 0x12000
	s_add_i32 s39, s38, 0x2000
	global_load_lds_dwordx4 v130, s[16:17]
	s_mov_b32 m0, s38
	s_add_u32 s6, s16, 0x40000
	global_load_lds_dwordx4 v134, s[12:13]
	s_mov_b32 m0, s39
	s_addc_u32 s7, s17, 0
	global_load_lds_dwordx4 v132, s[12:13]
	s_add_i32 m0, s38, 0x14000
	v_mov_b32_e32 v131, v17
	global_load_lds_dwordx4 v16, s[6:7]
	s_add_i32 m0, s38, 0x16000
	v_mov_b32_e32 v135, v17
	global_load_lds_dwordx4 v130, s[6:7]
	s_add_u32 s6, s12, 0x40000
	s_addc_u32 s7, s13, 0
	s_add_i32 s40, s38, 0x4000
	s_mov_b32 m0, s40
	s_add_i32 s41, s38, 0x6000
	global_load_lds_dwordx4 v134, s[6:7]
	s_mov_b32 m0, s41
	v_mov_b32_e32 v133, v17
	global_load_lds_dwordx4 v132, s[6:7]
	v_lshl_add_u64 v[6:7], s[16:17], 0, v[16:17]
	v_lshl_add_u64 v[4:5], s[16:17], 0, v[130:131]
	v_lshl_add_u64 v[2:3], s[12:13], 0, v[134:135]
	s_cmp_lg_u32 s1, 1
	v_lshl_add_u64 v[0:1], s[12:13], 0, v[132:133]
	s_cbranch_scc1 .LBB0_954
	s_barrier

.Llru_entry:
	s_lshl_b64 s[0:1], s[96:97], 18
	v_readlane_b32 s2, v252, 44
	s_add_u32 s0, s2, s0
	v_readlane_b32 s2, v252, 45
	s_addc_u32 s1, s2, s1
	s_lshl_b64 s[4:5], s[96:97], 17
	v_readlane_b32 s2, v252, 46
	s_add_u32 s4, s2, s4
	v_readlane_b32 s2, v252, 47
	s_addc_u32 s5, s2, s5
	v_lshlrev_b32_e32 v0, 3, v232
	v_lshlrev_b32_e32 v1, 2, v232
	global_load_dwordx2 v[20:21], v0, s[0:1]
	v_add_u32_e32 v0, 0x1000, v0
	global_load_dwordx2 v[22:23], v0, s[0:1]
	v_add_u32_e32 v0, 0x1000, v0
	global_load_dwordx2 v[24:25], v0, s[0:1]
	v_add_u32_e32 v0, 0x1000, v0
	global_load_dwordx2 v[26:27], v0, s[0:1]
	v_add_u32_e32 v0, 0x1000, v0
	global_load_dwordx2 v[28:29], v0, s[0:1]
	v_add_u32_e32 v0, 0x1000, v0
	global_load_dwordx2 v[30:31], v0, s[0:1]
	v_add_u32_e32 v0, 0x1000, v0
	global_load_dwordx2 v[32:33], v0, s[0:1]
	v_add_u32_e32 v0, 0x1000, v0
	global_load_dwordx2 v[34:35], v0, s[0:1]
	v_add_u32_e32 v0, 0x1000, v0
	global_load_dwordx2 v[36:37], v0, s[0:1]
	v_add_u32_e32 v0, 0x1000, v0
	global_load_dwordx2 v[38:39], v0, s[0:1]
	v_add_u32_e32 v0, 0x1000, v0
	global_load_dwordx2 v[40:41], v0, s[0:1]
	v_add_u32_e32 v0, 0x1000, v0
	global_load_dwordx2 v[42:43], v0, s[0:1]
	v_add_u32_e32 v0, 0x1000, v0
	global_load_dwordx2 v[44:45], v0, s[0:1]
	v_add_u32_e32 v0, 0x1000, v0
	global_load_dwordx2 v[46:47], v0, s[0:1]
	v_add_u32_e32 v0, 0x1000, v0
	global_load_dwordx2 v[48:49], v0, s[0:1]
	v_add_u32_e32 v0, 0x1000, v0
	global_load_dwordx2 v[50:51], v0, s[0:1]
	v_add_u32_e32 v0, 0x1000, v0
	global_load_dwordx2 v[52:53], v0, s[0:1]
	v_add_u32_e32 v0, 0x1000, v0
	global_load_dwordx2 v[54:55], v0, s[0:1]
	v_add_u32_e32 v0, 0x1000, v0
	global_load_dwordx2 v[56:57], v0, s[0:1]
	v_add_u32_e32 v0, 0x1000, v0
	global_load_dwordx2 v[58:59], v0, s[0:1]
	v_add_u32_e32 v0, 0x1000, v0
	global_load_dwordx2 v[60:61], v0, s[0:1]
	v_add_u32_e32 v0, 0x1000, v0
	global_load_dwordx2 v[62:63], v0, s[0:1]
	v_add_u32_e32 v0, 0x1000, v0
	global_load_dwordx2 v[64:65], v0, s[0:1]
	v_add_u32_e32 v0, 0x1000, v0
	global_load_dwordx2 v[66:67], v0, s[0:1]
	v_add_u32_e32 v0, 0x1000, v0
	global_load_dwordx2 v[68:69], v0, s[0:1]
	v_add_u32_e32 v0, 0x1000, v0
	global_load_dwordx2 v[70:71], v0, s[0:1]
	v_add_u32_e32 v0, 0x1000, v0
	global_load_dwordx2 v[72:73], v0, s[0:1]
	v_add_u32_e32 v0, 0x1000, v0
	global_load_dwordx2 v[74:75], v0, s[0:1]
	v_add_u32_e32 v0, 0x1000, v0
	global_load_dwordx2 v[76:77], v0, s[0:1]
	v_add_u32_e32 v0, 0x1000, v0
	global_load_dwordx2 v[78:79], v0, s[0:1]
	v_add_u32_e32 v0, 0x1000, v0
	global_load_dwordx2 v[80:81], v0, s[0:1]
	v_add_u32_e32 v0, 0x1000, v0
	global_load_dwordx2 v[82:83], v0, s[0:1]
	v_add_u32_e32 v0, 0x1000, v0
	global_load_dwordx2 v[84:85], v0, s[0:1]
	v_add_u32_e32 v0, 0x1000, v0
	global_load_dwordx2 v[86:87], v0, s[0:1]
	v_add_u32_e32 v0, 0x1000, v0
	global_load_dwordx2 v[88:89], v0, s[0:1]
	v_add_u32_e32 v0, 0x1000, v0
	global_load_dwordx2 v[90:91], v0, s[0:1]
	v_add_u32_e32 v0, 0x1000, v0
	global_load_dwordx2 v[92:93], v0, s[0:1]
	v_add_u32_e32 v0, 0x1000, v0
	global_load_dwordx2 v[94:95], v0, s[0:1]
	v_add_u32_e32 v0, 0x1000, v0
	global_load_dwordx2 v[96:97], v0, s[0:1]
	v_add_u32_e32 v0, 0x1000, v0
	global_load_dwordx2 v[98:99], v0, s[0:1]
	v_add_u32_e32 v0, 0x1000, v0
	global_load_dwordx2 v[100:101], v0, s[0:1]
	v_add_u32_e32 v0, 0x1000, v0
	global_load_dwordx2 v[102:103], v0, s[0:1]
	v_add_u32_e32 v0, 0x1000, v0
	global_load_dwordx2 v[104:105], v0, s[0:1]
	v_add_u32_e32 v0, 0x1000, v0
	global_load_dwordx2 v[106:107], v0, s[0:1]
	v_add_u32_e32 v0, 0x1000, v0
	global_load_dwordx2 v[108:109], v0, s[0:1]
	v_add_u32_e32 v0, 0x1000, v0
	global_load_dwordx2 v[110:111], v0, s[0:1]
	v_add_u32_e32 v0, 0x1000, v0
	global_load_dwordx2 v[112:113], v0, s[0:1]
	v_add_u32_e32 v0, 0x1000, v0
	global_load_dwordx2 v[114:115], v0, s[0:1]
	v_add_u32_e32 v0, 0x1000, v0
	global_load_dwordx2 v[116:117], v0, s[0:1]
	v_add_u32_e32 v0, 0x1000, v0
	global_load_dwordx2 v[118:119], v0, s[0:1]
	v_add_u32_e32 v0, 0x1000, v0
	global_load_dwordx2 v[120:121], v0, s[0:1]
	v_add_u32_e32 v0, 0x1000, v0
	global_load_dwordx2 v[122:123], v0, s[0:1]
	v_add_u32_e32 v0, 0x1000, v0
	global_load_dwordx2 v[124:125], v0, s[0:1]
	v_add_u32_e32 v0, 0x1000, v0
	global_load_dwordx2 v[126:127], v0, s[0:1]
	v_add_u32_e32 v0, 0x1000, v0
	global_load_dwordx2 v[128:129], v0, s[0:1]
	v_add_u32_e32 v0, 0x1000, v0
	global_load_dwordx2 v[130:131], v0, s[0:1]
	v_add_u32_e32 v0, 0x1000, v0
	global_load_dwordx2 v[132:133], v0, s[0:1]
	v_add_u32_e32 v0, 0x1000, v0
	global_load_dwordx2 v[134:135], v0, s[0:1]
	v_add_u32_e32 v0, 0x1000, v0
	global_load_dwordx2 v[136:137], v0, s[0:1]
	v_add_u32_e32 v0, 0x1000, v0
	global_load_dwordx2 v[138:139], v0, s[0:1]
	v_add_u32_e32 v0, 0x1000, v0
	global_load_dwordx2 v[140:141], v0, s[0:1]
	v_add_u32_e32 v0, 0x1000, v0
	global_load_dwordx2 v[142:143], v0, s[0:1]
	v_add_u32_e32 v0, 0x1000, v0
	v_mov_b32_e32 v2, 0
	s_waitcnt vmcnt(60)
	v_fmac_f32_e32 v21, v20, v2
	v_fmac_f32_e32 v23, v22, v21
	global_load_dwordx2 v[144:145], v0, s[0:1]
	v_add_u32_e32 v0, 0x1000, v0
	global_load_dwordx2 v[146:147], v0, s[0:1]
	v_add_u32_e32 v0, 0x1000, v0
	s_waitcnt vmcnt(61)
	v_fmac_f32_e32 v25, v24, v23
	s_waitcnt vmcnt(60)
	v_fmac_f32_e32 v27, v26, v25
	s_waitcnt vmcnt(59)
	v_fmac_f32_e32 v29, v28, v27
	s_waitcnt vmcnt(58)
	v_fmac_f32_e32 v31, v30, v29
	s_waitcnt vmcnt(57)
	v_fmac_f32_e32 v33, v32, v31
	s_waitcnt vmcnt(56)
	v_fmac_f32_e32 v35, v34, v33
	s_waitcnt vmcnt(55)
	v_fmac_f32_e32 v37, v36, v35
	s_waitcnt vmcnt(54)
	v_fmac_f32_e32 v39, v38, v37
	s_waitcnt vmcnt(53)
	v_fmac_f32_e32 v41, v40, v39
	s_waitcnt vmcnt(52)
	v_fmac_f32_e32 v43, v42, v41
	s_waitcnt vmcnt(51)
	v_fmac_f32_e32 v45, v44, v43
	s_waitcnt vmcnt(50)
	v_fmac_f32_e32 v47, v46, v45
	s_waitcnt vmcnt(49)
	v_fmac_f32_e32 v49, v48, v47
	s_waitcnt vmcnt(48)
	v_fmac_f32_e32 v51, v50, v49
	s_waitcnt vmcnt(47)
	v_fmac_f32_e32 v53, v52, v51
	s_waitcnt vmcnt(46)
	v_fmac_f32_e32 v55, v54, v53
	s_waitcnt vmcnt(45)
	v_fmac_f32_e32 v57, v56, v55
	s_waitcnt vmcnt(44)
	v_fmac_f32_e32 v59, v58, v57
	s_waitcnt vmcnt(43)
	v_fmac_f32_e32 v61, v60, v59
	s_waitcnt vmcnt(42)
	v_fmac_f32_e32 v63, v62, v61
	s_waitcnt vmcnt(41)
	v_fmac_f32_e32 v65, v64, v63
	s_waitcnt vmcnt(40)
	v_fmac_f32_e32 v67, v66, v65
	s_waitcnt vmcnt(39)
	v_fmac_f32_e32 v69, v68, v67
	s_waitcnt vmcnt(38)
	v_fmac_f32_e32 v71, v70, v69
	s_waitcnt vmcnt(37)
	v_fmac_f32_e32 v73, v72, v71
	s_waitcnt vmcnt(36)
	v_fmac_f32_e32 v75, v74, v73
	s_waitcnt vmcnt(35)
	v_fmac_f32_e32 v77, v76, v75
	s_waitcnt vmcnt(34)
	v_fmac_f32_e32 v79, v78, v77
	s_waitcnt vmcnt(33)
	v_fmac_f32_e32 v81, v80, v79
	s_waitcnt vmcnt(32)
	v_fmac_f32_e32 v83, v82, v81
	s_waitcnt vmcnt(31)
	v_fmac_f32_e32 v85, v84, v83
	s_waitcnt vmcnt(30)
	v_fmac_f32_e32 v87, v86, v85
	s_waitcnt vmcnt(29)
	v_fmac_f32_e32 v89, v88, v87
	s_waitcnt vmcnt(28)
	v_fmac_f32_e32 v91, v90, v89
	s_waitcnt vmcnt(27)
	v_fmac_f32_e32 v93, v92, v91
	s_waitcnt vmcnt(26)
	v_fmac_f32_e32 v95, v94, v93
	s_waitcnt vmcnt(25)
	v_fmac_f32_e32 v97, v96, v95
	s_waitcnt vmcnt(24)
	v_fmac_f32_e32 v99, v98, v97
	s_waitcnt vmcnt(23)
	v_fmac_f32_e32 v101, v100, v99
	s_waitcnt vmcnt(22)
	v_fmac_f32_e32 v103, v102, v101
	s_waitcnt vmcnt(21)
	v_fmac_f32_e32 v105, v104, v103
	s_waitcnt vmcnt(20)
	v_fmac_f32_e32 v107, v106, v105
	s_waitcnt vmcnt(19)
	v_fmac_f32_e32 v109, v108, v107
	s_waitcnt vmcnt(18)
	v_fmac_f32_e32 v111, v110, v109
	s_waitcnt vmcnt(17)
	v_fmac_f32_e32 v113, v112, v111
	s_waitcnt vmcnt(16)
	v_fmac_f32_e32 v115, v114, v113
	s_waitcnt vmcnt(15)
	v_fmac_f32_e32 v117, v116, v115
	s_waitcnt vmcnt(14)
	v_fmac_f32_e32 v119, v118, v117
	s_waitcnt vmcnt(13)
	v_fmac_f32_e32 v121, v120, v119
	s_waitcnt vmcnt(12)
	v_fmac_f32_e32 v123, v122, v121
	s_waitcnt vmcnt(11)
	v_fmac_f32_e32 v125, v124, v123
	s_waitcnt vmcnt(10)
	v_fmac_f32_e32 v127, v126, v125
	s_waitcnt vmcnt(9)
	v_fmac_f32_e32 v129, v128, v127
	s_waitcnt vmcnt(8)
	v_fmac_f32_e32 v131, v130, v129
	s_waitcnt vmcnt(7)
	v_fmac_f32_e32 v133, v132, v131
	s_waitcnt vmcnt(6)
	v_fmac_f32_e32 v135, v134, v133
	s_waitcnt vmcnt(5)
	v_fmac_f32_e32 v137, v136, v135
	s_waitcnt vmcnt(4)
	v_fmac_f32_e32 v139, v138, v137
	s_waitcnt vmcnt(3)
	v_fmac_f32_e32 v141, v140, v139
	s_waitcnt vmcnt(2)
	v_fmac_f32_e32 v143, v142, v141
	s_waitcnt vmcnt(1)
	v_fmac_f32_e32 v145, v144, v143
	s_waitcnt vmcnt(0)
	v_fmac_f32_e32 v147, v146, v145
	global_store_dword v1, v2, s[4:5]
	v_add_u32_e32 v1, 0x800, v1
	global_store_dword v1, v21, s[4:5]
	v_add_u32_e32 v1, 0x800, v1
	global_store_dword v1, v23, s[4:5]
	v_add_u32_e32 v1, 0x800, v1
	global_store_dword v1, v25, s[4:5]
	v_add_u32_e32 v1, 0x800, v1
	global_store_dword v1, v27, s[4:5]
	v_add_u32_e32 v1, 0x800, v1
	global_store_dword v1, v29, s[4:5]
	v_add_u32_e32 v1, 0x800, v1
	global_store_dword v1, v31, s[4:5]
	v_add_u32_e32 v1, 0x800, v1
	global_store_dword v1, v33, s[4:5]
	v_add_u32_e32 v1, 0x800, v1
	global_store_dword v1, v35, s[4:5]
	v_add_u32_e32 v1, 0x800, v1
	global_store_dword v1, v37, s[4:5]
	v_add_u32_e32 v1, 0x800, v1
	global_store_dword v1, v39, s[4:5]
	v_add_u32_e32 v1, 0x800, v1
	global_store_dword v1, v41, s[4:5]
	v_add_u32_e32 v1, 0x800, v1
	global_store_dword v1, v43, s[4:5]
	v_add_u32_e32 v1, 0x800, v1
	global_store_dword v1, v45, s[4:5]
	v_add_u32_e32 v1, 0x800, v1
	global_store_dword v1, v47, s[4:5]
	v_add_u32_e32 v1, 0x800, v1
	global_store_dword v1, v49, s[4:5]
	v_add_u32_e32 v1, 0x800, v1
	global_store_dword v1, v51, s[4:5]
	v_add_u32_e32 v1, 0x800, v1
	global_store_dword v1, v53, s[4:5]
	v_add_u32_e32 v1, 0x800, v1
	global_store_dword v1, v55, s[4:5]
	v_add_u32_e32 v1, 0x800, v1
	global_store_dword v1, v57, s[4:5]
	v_add_u32_e32 v1, 0x800, v1
	global_store_dword v1, v59, s[4:5]
	v_add_u32_e32 v1, 0x800, v1
	global_store_dword v1, v61, s[4:5]
	v_add_u32_e32 v1, 0x800, v1
	global_store_dword v1, v63, s[4:5]
	v_add_u32_e32 v1, 0x800, v1
	global_store_dword v1, v65, s[4:5]
	v_add_u32_e32 v1, 0x800, v1
	global_store_dword v1, v67, s[4:5]
	v_add_u32_e32 v1, 0x800, v1
	global_store_dword v1, v69, s[4:5]
	v_add_u32_e32 v1, 0x800, v1
	global_store_dword v1, v71, s[4:5]
	v_add_u32_e32 v1, 0x800, v1
	global_store_dword v1, v73, s[4:5]
	v_add_u32_e32 v1, 0x800, v1
	global_store_dword v1, v75, s[4:5]
	v_add_u32_e32 v1, 0x800, v1
	global_store_dword v1, v77, s[4:5]
	v_add_u32_e32 v1, 0x800, v1
	global_store_dword v1, v79, s[4:5]
	v_add_u32_e32 v1, 0x800, v1
	global_store_dword v1, v81, s[4:5]
	v_add_u32_e32 v1, 0x800, v1
	global_store_dword v1, v83, s[4:5]
	v_add_u32_e32 v1, 0x800, v1
	s_waitcnt vmcnt(16)
	global_store_dword v1, v85, s[4:5]
	v_add_u32_e32 v1, 0x800, v1
	global_store_dword v1, v87, s[4:5]
	v_add_u32_e32 v1, 0x800, v1
	global_store_dword v1, v89, s[4:5]
	v_add_u32_e32 v1, 0x800, v1
	global_store_dword v1, v91, s[4:5]
	v_add_u32_e32 v1, 0x800, v1
	global_store_dword v1, v93, s[4:5]
	v_add_u32_e32 v1, 0x800, v1
	global_store_dword v1, v95, s[4:5]
	v_add_u32_e32 v1, 0x800, v1
	global_store_dword v1, v97, s[4:5]
	v_add_u32_e32 v1, 0x800, v1
	global_store_dword v1, v99, s[4:5]
	v_add_u32_e32 v1, 0x800, v1
	global_store_dword v1, v101, s[4:5]
	v_add_u32_e32 v1, 0x800, v1
	global_store_dword v1, v103, s[4:5]
	v_add_u32_e32 v1, 0x800, v1
	global_store_dword v1, v105, s[4:5]
	v_add_u32_e32 v1, 0x800, v1
	global_store_dword v1, v107, s[4:5]
	v_add_u32_e32 v1, 0x800, v1
	global_store_dword v1, v109, s[4:5]
	v_add_u32_e32 v1, 0x800, v1
	global_store_dword v1, v111, s[4:5]
	v_add_u32_e32 v1, 0x800, v1
	global_store_dword v1, v113, s[4:5]
	v_add_u32_e32 v1, 0x800, v1
	global_store_dword v1, v115, s[4:5]
	v_add_u32_e32 v1, 0x800, v1
	global_store_dword v1, v117, s[4:5]
	v_add_u32_e32 v1, 0x800, v1
	global_store_dword v1, v119, s[4:5]
	v_add_u32_e32 v1, 0x800, v1
	global_store_dword v1, v121, s[4:5]
	v_add_u32_e32 v1, 0x800, v1
	global_store_dword v1, v123, s[4:5]
	v_add_u32_e32 v1, 0x800, v1
	global_store_dword v1, v125, s[4:5]
	v_add_u32_e32 v1, 0x800, v1
	global_store_dword v1, v127, s[4:5]
	v_add_u32_e32 v1, 0x800, v1
	global_store_dword v1, v129, s[4:5]
	v_add_u32_e32 v1, 0x800, v1
	global_store_dword v1, v131, s[4:5]
	v_add_u32_e32 v1, 0x800, v1
	global_store_dword v1, v133, s[4:5]
	v_add_u32_e32 v1, 0x800, v1
	global_store_dword v1, v135, s[4:5]
	v_add_u32_e32 v1, 0x800, v1
	global_store_dword v1, v137, s[4:5]
	v_add_u32_e32 v1, 0x800, v1
	global_store_dword v1, v139, s[4:5]
	v_add_u32_e32 v1, 0x800, v1
	global_store_dword v1, v141, s[4:5]
	v_add_u32_e32 v1, 0x800, v1
	global_store_dword v1, v143, s[4:5]
	v_add_u32_e32 v1, 0x800, v1
	global_store_dword v1, v145, s[4:5]

.LBB0_983:
	v_cndmask_b32_e64 v16, 0, 1, s[6:7]
	v_cmp_ne_u32_e64 s[0:1], 1, v16
	s_andn2_b64 vcc, exec, s[6:7]
	v_lshl_add_u64 v[18:19], s[82:83], 0, v[84:85]
	s_cbranch_vccnz .LBB0_985
	v_add_u32_e32 v16, v87, v91
	v_add_co_u32_e32 v106, vcc, s77, v18
	s_nop 1
	v_addc_co_u32_e32 v107, vcc, 0, v19, vcc
	ds_read_b128 v[72:75], v92 offset:45056
	ds_read_b128 v[68:71], v92 offset:45120
	ds_read_b128 v[108:111], v87 offset:63488
	ds_read_b128 v[112:115], v87 offset:63552
	ds_read_b128 v[116:119], v87 offset:63616
	ds_read_b128 v[120:123], v87 offset:63680
	ds_read_b128 v[124:127], v16 offset:17408
	ds_read_b128 v[128:131], v16
	ds_read_b128 v[132:135], v16 offset:64
	ds_read_b128 v[136:139], v16 offset:19712
	ds_read_b128 v[140:143], v16 offset:2304
	s_waitcnt lgkmcnt(8)
	v_pk_mul_f32 v[110:111], v[54:55], v[110:111]
	v_pk_mul_f32 v[108:109], v[52:53], v[108:109]
	ds_read_b128 v[144:147], v16 offset:2368
	s_waitcnt lgkmcnt(8)
	v_pk_mul_f32 v[114:115], v[58:59], v[114:115]
	v_pk_mul_f32 v[112:113], v[56:57], v[112:113]
	v_cvt_pk_bf16_f32 v76, v108, v109
	v_cvt_pk_bf16_f32 v77, v110, v111
	v_cvt_pk_bf16_f32 v78, v112, v113
	v_cvt_pk_bf16_f32 v79, v114, v115
	ds_read_b128 v[148:151], v16 offset:22016
	s_waitcnt lgkmcnt(8)
	v_pk_mul_f32 v[118:119], v[62:63], v[118:119]
	v_pk_mul_f32 v[116:117], v[60:61], v[116:117]
	ds_read_b128 v[152:155], v16 offset:22080
	s_waitcnt lgkmcnt(8)
	v_pk_mul_f32 v[122:123], v[66:67], v[122:123]
	v_pk_mul_f32 v[120:121], v[64:65], v[120:121]
	v_cvt_pk_bf16_f32 v80, v116, v117
	v_cvt_pk_bf16_f32 v81, v118, v119
	v_cvt_pk_bf16_f32 v82, v120, v121
	v_cvt_pk_bf16_f32 v83, v122, v123
	ds_read_b128 v[108:111], v16 offset:4608
	s_waitcnt lgkmcnt(8)
	v_mfma_f32_16x16x32_bf16 v[156:159], v[124:127], v[72:75], 0
	ds_read_b128 v[112:115], v16 offset:4672
	s_waitcnt lgkmcnt(8)
	v_mfma_f32_16x16x32_bf16 v[156:159], v[128:131], v[76:79], v[156:159]
	ds_read_b128 v[116:119], v16 offset:24320
	s_waitcnt lgkmcnt(8)
	v_mfma_f32_16x16x32_bf16 v[156:159], v[132:135], v[80:83], v[156:159]
	ds_read_b128 v[120:123], v16 offset:24384
	s_waitcnt lgkmcnt(8)
	v_mfma_f32_16x16x32_bf16 v[160:163], v[136:139], v[72:75], 0
	ds_read_b128 v[124:127], v16 offset:6912
	s_waitcnt lgkmcnt(8)
	v_mfma_f32_16x16x32_bf16 v[160:163], v[140:143], v[76:79], v[160:163]
	ds_read_b128 v[128:131], v16 offset:6976
	s_waitcnt lgkmcnt(8)
	v_mfma_f32_16x16x32_bf16 v[160:163], v[144:147], v[80:83], v[160:163]
	v_cvt_pk_bf16_f32 v164, v156, v157
	v_cvt_pk_bf16_f32 v165, v158, v159
	global_store_dwordx2 v[106:107], v[164:165], off
	ds_read_b128 v[132:135], v16 offset:26624
	s_waitcnt lgkmcnt(8)
	v_mfma_f32_16x16x32_bf16 v[156:159], v[148:151], v[72:75], 0
	ds_read_b128 v[136:139], v16 offset:26688
	s_waitcnt lgkmcnt(8)
	v_mfma_f32_16x16x32_bf16 v[156:159], v[152:155], v[68:71], v[156:159]
	ds_read_b128 v[140:143], v87 offset:64000
	s_waitcnt lgkmcnt(8)
	v_mfma_f32_16x16x32_bf16 v[156:159], v[108:111], v[76:79], v[156:159]
	ds_read_b128 v[144:147], v87 offset:63744
	s_waitcnt lgkmcnt(8)
	v_mfma_f32_16x16x32_bf16 v[156:159], v[112:115], v[80:83], v[156:159]
	v_cvt_pk_bf16_f32 v166, v160, v161
	v_cvt_pk_bf16_f32 v167, v162, v163
	global_store_dwordx2 v[106:107], v[166:167], off offset:32
	ds_read_b128 v[148:151], v16 offset:28928
	s_waitcnt lgkmcnt(8)
	v_mfma_f32_16x16x32_bf16 v[160:163], v[116:119], v[72:75], 0
	ds_read_b128 v[152:155], v16 offset:28992
	s_waitcnt lgkmcnt(8)
	v_mfma_f32_16x16x32_bf16 v[160:163], v[120:123], v[68:71], v[160:163]
	ds_read_b128 v[108:111], v87 offset:64064
	s_waitcnt lgkmcnt(8)
	v_mfma_f32_16x16x32_bf16 v[160:163], v[124:127], v[76:79], v[160:163]
	ds_read_b128 v[112:115], v87 offset:63808
	s_waitcnt lgkmcnt(8)
	v_mfma_f32_16x16x32_bf16 v[160:163], v[128:131], v[80:83], v[160:163]
	v_cvt_pk_bf16_f32 v168, v156, v157
	v_cvt_pk_bf16_f32 v169, v158, v159
	global_store_dwordx2 v[106:107], v[168:169], off offset:64
	ds_read_b128 v[116:119], v16 offset:31232
	s_waitcnt lgkmcnt(8)
	v_mfma_f32_16x16x32_bf16 v[188:191], v[132:135], v[72:75], 0
	ds_read_b128 v[120:123], v16 offset:31296
	s_waitcnt lgkmcnt(8)
	v_mfma_f32_16x16x32_bf16 v[188:191], v[136:139], v[68:71], v[188:191]
	ds_read_b128 v[124:127], v87 offset:64128
	ds_read_b128 v[128:131], v87 offset:63872
	ds_read_b128 v[132:135], v16 offset:33536
	s_waitcnt lgkmcnt(8)
	v_mfma_f32_16x16x32_bf16 v[192:195], v[148:151], v[72:75], 0
	ds_read_b128 v[136:139], v16 offset:33600
	s_waitcnt lgkmcnt(8)
	v_mfma_f32_16x16x32_bf16 v[192:195], v[152:155], v[68:71], v[192:195]
	v_cvt_pk_bf16_f32 v170, v160, v161
	v_cvt_pk_bf16_f32 v171, v162, v163
	global_store_dwordx2 v[106:107], v[170:171], off offset:96
	ds_read_b128 v[148:151], v87 offset:64192
	ds_read_b128 v[152:155], v87 offset:63936
	s_waitcnt lgkmcnt(7)
	v_mfma_f32_16x16x32_bf16 v[196:199], v[116:119], v[72:75], 0
	s_waitcnt lgkmcnt(6)
	v_mfma_f32_16x16x32_bf16 v[196:199], v[120:123], v[68:71], v[196:199]
	v_pk_mul_f32 v[146:147], v[190:191], v[146:147]
	v_pk_mul_f32 v[144:145], v[188:189], v[144:145]
	v_pk_fma_f32 v[54:55], v[54:55], v[142:143], v[146:147]
	v_pk_fma_f32 v[52:53], v[52:53], v[140:141], v[144:145]
	s_waitcnt lgkmcnt(3)
	v_mfma_f32_16x16x32_bf16 v[188:191], v[132:135], v[72:75], 0
	s_waitcnt lgkmcnt(2)
	v_mfma_f32_16x16x32_bf16 v[188:191], v[136:139], v[68:71], v[188:191]
	v_pk_mul_f32 v[114:115], v[194:195], v[114:115]
	v_pk_mul_f32 v[112:113], v[192:193], v[112:113]
	v_pk_fma_f32 v[58:59], v[58:59], v[110:111], v[114:115]
	v_pk_fma_f32 v[56:57], v[56:57], v[108:109], v[112:113]
	v_pk_mul_f32 v[130:131], v[198:199], v[130:131]
	v_pk_mul_f32 v[128:129], v[196:197], v[128:129]
	v_pk_fma_f32 v[62:63], v[62:63], v[126:127], v[130:131]
	v_pk_fma_f32 v[60:61], v[60:61], v[124:125], v[128:129]
	s_waitcnt lgkmcnt(0)
	v_pk_mul_f32 v[154:155], v[190:191], v[154:155]
	v_pk_mul_f32 v[152:153], v[188:189], v[152:153]
	v_pk_fma_f32 v[66:67], v[66:67], v[150:151], v[154:155]
	v_pk_fma_f32 v[64:65], v[64:65], v[148:149], v[152:153]
.LBB0_985:
	v_mov_b32_e32 v72, v86
	s_mov_b32 s8, 0xffffffe
	v_ashrrev_i32_e32 v16, 31, v72
	v_lshrrev_b32_e32 v16, 29, v16
	v_add_u32_e32 v68, v72, v16
	v_lshrrev_b32_e32 v16, 3, v68
	v_add_u32_e32 v75, 0x200, v72
	v_and_b32_e32 v68, 0xffffff8, v68
	v_ashrrev_i32_e32 v70, 3, v72
	v_bfe_u32 v73, v72, 3, 1
	v_lshrrev_b32_e32 v75, 3, v75
	v_sub_u32_e32 v68, v72, v68
	v_mul_lo_u32 v69, v16, s63
	v_lshlrev_b32_e32 v16, 4, v72
	v_and_or_b32 v74, v70, s8, v73
	v_and_or_b32 v73, v75, s8, v73
	v_lshlrev_b32_e32 v68, 4, v68
	v_readlane_b32 s8, v254, 40
	v_and_b32_e32 v71, 0x70, v16
	v_cmp_gt_i32_e32 vcc, 48, v72
	v_add3_u32 v68, s8, v69, v68
	s_cmp_eq_u32 s17, 0
	s_cbranch_scc1 .Lgla_w8
	s_cmp_eq_u32 s17, 62
	s_cbranch_scc1 .Lgla_w8
	s_waitcnt vmcnt(13)
	s_branch .Lgla_wd
.Lgla_w8:
	s_waitcnt vmcnt(8)
.Lgla_wd:
	ds_write_b128 v68, v[4:7]
	v_add_u32_e32 v68, s8, v71
	v_mad_u64_u32 v[70:71], s[8:9], v70, s63, v[68:69]
	ds_write_b128 v70, v[8:11] offset:17408
	ds_write_b128 v70, v[12:15] offset:26624
	v_mad_u64_u32 v[70:71], s[8:9], v74, s63, v[68:69]
	v_mad_u64_u32 v[68:69], s[8:9], v73, s63, v[68:69]
	ds_write_b128 v70, v[20:23] offset:45056
	ds_write_b128 v68, v[24:27] offset:45056
	s_and_saveexec_b64 s[8:9], vcc
	v_add_u32_e32 v16, 0, v16
	v_add_u32_e32 v16, 0x1fc00, v16
	ds_write_b128 v16, v[0:3]
	s_or_b64 exec, exec, s[8:9]
	s_cmp_gt_u32 s17, 60
	s_cbranch_scc1 .LBB0_991
	v_mov_b32_e32 v68, v86
	s_mov_b32 s20, 0x2a0000
	v_ashrrev_i32_e32 v4, 31, v68
	v_lshrrev_b32_e32 v4, 29, v4
	v_add_u32_e32 v4, v68, v4
	v_lshrrev_b32_e32 v5, 3, v4
	v_and_b32_e32 v4, 0x1ffffff8, v4
	v_sub_u32_e32 v4, v68, v4
	v_lshlrev_b32_e32 v6, 3, v4
	v_lshrrev_b32_e32 v4, 3, v68
	v_mul_lo_u32 v7, v4, s60
	v_lshlrev_b32_e32 v4, 3, v68
	v_and_b32_e32 v8, 56, v4
	v_and_b32_e32 v4, 0x78, v4
	v_mul_lo_u32 v5, v5, s60
	v_or_b32_e32 v4, s12, v4
	v_lshrrev_b32_e32 v10, 4, v68
	v_mad_u64_u32 v[12:13], s[8:9], v10, s60, v[4:5]
	v_add_u32_e32 v10, 0x200, v68
	v_lshrrev_b32_e32 v10, 4, v10
	v_mad_u64_u32 v[24:25], s[8:9], v10, s60, v[4:5]
	s_add_u32 s8, s82, s4
	v_add3_u32 v16, v5, s11, v6
	s_addc_u32 s9, s83, s5
	v_add_u32_e32 v9, s13, v7
	v_add_u32_e32 v4, s16, v7
	v_lshl_add_u64 v[6:7], v[16:17], 1, s[8:9]
	v_or_b32_e32 v4, v4, v8
	v_add_co_u32_e32 v6, vcc, s20, v6
	v_mov_b32_e32 v5, v17
	s_nop 0
	v_addc_co_u32_e32 v7, vcc, 0, v7, vcc
	v_lshl_add_u64 v[4:5], v[4:5], 1, s[8:9]
	v_or_b32_e32 v14, v9, v8
	v_add_co_u32_e32 v8, vcc, s20, v4
	v_mov_b32_e32 v15, v17
	s_nop 0
	v_addc_co_u32_e32 v9, vcc, 0, v5, vcc
	v_lshl_add_u64 v[14:15], v[14:15], 1, s[8:9]
	v_add_co_u32_e32 v14, vcc, s20, v14
	v_mov_b32_e32 v13, v17
	s_nop 0
	v_addc_co_u32_e32 v15, vcc, 0, v15, vcc
	v_lshl_add_u64 v[12:13], v[12:13], 1, s[8:9]
	v_add_co_u32_e32 v20, vcc, 0x2a0000, v12
	v_mov_b32_e32 v25, v17
	s_nop 0
	v_addc_co_u32_e32 v21, vcc, 0, v13, vcc
	v_lshl_add_u64 v[24:25], v[24:25], 1, s[8:9]
	v_add_co_u32_e32 v24, vcc, 0x2a0000, v24
	global_load_dwordx4 v[4:7], v[6:7], off
	s_nop 0
	global_load_dwordx4 v[8:11], v[8:9], off
	v_addc_co_u32_e32 v25, vcc, 0, v25, vcc
	global_load_dwordx4 v[12:15], v[14:15], off
	s_nop 0
	global_load_dwordx4 v[20:23], v[20:21], off
	v_cmp_gt_i32_e32 vcc, 48, v68
	global_load_dwordx4 v[24:27], v[24:25], off
	s_and_saveexec_b64 s[8:9], vcc
	s_cbranch_execz .LBB0_990
	v_lshlrev_b32_e32 v0, 2, v68
	s_add_u32 s20, s82, s10
	v_ashrrev_i32_e32 v1, 31, v0
	s_addc_u32 s21, s83, s2
	v_lshl_add_u64 v[0:1], v[0:1], 2, s[20:21]
	v_add_co_u32_e32 v0, vcc, 0x1f7c0000, v0
	s_nop 1
	v_addc_co_u32_e32 v1, vcc, 0, v1, vcc
	global_load_dwordx4 v[0:3], v[0:1], off offset:2304

.LBB0_994:
	s_mov_b32 s0, 0xe2000
	v_add_co_u32_e32 v18, vcc, s0, v18
	s_nop 1
	v_addc_co_u32_e32 v19, vcc, 0, v19, vcc
	ds_read_b128 v[72:75], v93
	ds_read_b128 v[68:71], v93 offset:64
	ds_read_b128 v[108:111], v88
	ds_read_b128 v[112:115], v88 offset:64
	ds_read_b128 v[116:119], v88 offset:128
	ds_read_b128 v[120:123], v88 offset:192
	ds_read_b128 v[124:127], v94
	ds_read_b128 v[128:131], v95
	ds_read_b128 v[132:135], v95 offset:64
	ds_read_b128 v[136:139], v94 offset:2304
	ds_read_b128 v[140:143], v95 offset:2304
	s_waitcnt lgkmcnt(8)
	v_pk_mul_f32 v[110:111], v[54:55], v[110:111]
	v_pk_mul_f32 v[108:109], v[52:53], v[108:109]
	ds_read_b128 v[144:147], v95 offset:2368
	s_waitcnt lgkmcnt(8)
	v_pk_mul_f32 v[114:115], v[58:59], v[114:115]
	v_pk_mul_f32 v[112:113], v[56:57], v[112:113]
	v_cvt_pk_bf16_f32 v76, v108, v109
	v_cvt_pk_bf16_f32 v77, v110, v111
	v_cvt_pk_bf16_f32 v78, v112, v113
	v_cvt_pk_bf16_f32 v79, v114, v115
	ds_read_b128 v[148:151], v94 offset:4608
	s_waitcnt lgkmcnt(8)
	v_pk_mul_f32 v[118:119], v[62:63], v[118:119]
	v_pk_mul_f32 v[116:117], v[60:61], v[116:117]
	ds_read_b128 v[152:155], v94 offset:4672
	s_waitcnt lgkmcnt(8)
	v_pk_mul_f32 v[122:123], v[66:67], v[122:123]
	v_pk_mul_f32 v[120:121], v[64:65], v[120:121]
	v_cvt_pk_bf16_f32 v80, v116, v117
	v_cvt_pk_bf16_f32 v81, v118, v119
	v_cvt_pk_bf16_f32 v82, v120, v121
	v_cvt_pk_bf16_f32 v83, v122, v123
	ds_read_b128 v[108:111], v95 offset:4608
	s_waitcnt lgkmcnt(8)
	v_mfma_f32_16x16x32_bf16 v[156:159], v[124:127], v[72:75], 0
	ds_read_b128 v[112:115], v95 offset:4672
	s_waitcnt lgkmcnt(8)
	v_mfma_f32_16x16x32_bf16 v[156:159], v[128:131], v[76:79], v[156:159]
	ds_read_b128 v[116:119], v94 offset:6912
	s_waitcnt lgkmcnt(8)
	v_mfma_f32_16x16x32_bf16 v[156:159], v[132:135], v[80:83], v[156:159]
	ds_read_b128 v[120:123], v94 offset:6976
	s_waitcnt lgkmcnt(8)
	v_mfma_f32_16x16x32_bf16 v[160:163], v[136:139], v[72:75], 0
	ds_read_b128 v[124:127], v95 offset:6912
	s_waitcnt lgkmcnt(8)
	v_mfma_f32_16x16x32_bf16 v[160:163], v[140:143], v[76:79], v[160:163]
	ds_read_b128 v[128:131], v95 offset:6976
	s_waitcnt lgkmcnt(8)
	v_mfma_f32_16x16x32_bf16 v[160:163], v[144:147], v[80:83], v[160:163]
	v_cvt_pk_bf16_f32 v164, v156, v157
	v_cvt_pk_bf16_f32 v165, v158, v159
	global_store_dwordx2 v[18:19], v[164:165], off
	ds_read_b128 v[132:135], v96
	s_waitcnt lgkmcnt(8)
	v_mfma_f32_16x16x32_bf16 v[156:159], v[148:151], v[72:75], 0
	ds_read_b128 v[136:139], v96 offset:64
	s_waitcnt lgkmcnt(8)
	v_mfma_f32_16x16x32_bf16 v[156:159], v[152:155], v[68:71], v[156:159]
	ds_read_b128 v[140:143], v89
	s_waitcnt lgkmcnt(8)
	v_mfma_f32_16x16x32_bf16 v[156:159], v[108:111], v[76:79], v[156:159]
	ds_read_b128 v[144:147], v90
	s_waitcnt lgkmcnt(8)
	v_mfma_f32_16x16x32_bf16 v[156:159], v[112:115], v[80:83], v[156:159]
	v_cvt_pk_bf16_f32 v166, v160, v161
	v_cvt_pk_bf16_f32 v167, v162, v163
	global_store_dwordx2 v[18:19], v[166:167], off offset:32
	ds_read_b128 v[148:151], v96 offset:2304
	s_waitcnt lgkmcnt(8)
	v_mfma_f32_16x16x32_bf16 v[160:163], v[116:119], v[72:75], 0
	ds_read_b128 v[152:155], v96 offset:2368
	s_waitcnt lgkmcnt(8)
	v_mfma_f32_16x16x32_bf16 v[160:163], v[120:123], v[68:71], v[160:163]
	ds_read_b128 v[108:111], v89 offset:64
	s_waitcnt lgkmcnt(8)
	v_mfma_f32_16x16x32_bf16 v[160:163], v[124:127], v[76:79], v[160:163]
	ds_read_b128 v[112:115], v90 offset:64
	s_waitcnt lgkmcnt(8)
	v_mfma_f32_16x16x32_bf16 v[160:163], v[128:131], v[80:83], v[160:163]
	v_cvt_pk_bf16_f32 v168, v156, v157
	v_cvt_pk_bf16_f32 v169, v158, v159
	global_store_dwordx2 v[18:19], v[168:169], off offset:64
	ds_read_b128 v[116:119], v96 offset:4608
	s_waitcnt lgkmcnt(8)
	v_mfma_f32_16x16x32_bf16 v[188:191], v[132:135], v[72:75], 0
	ds_read_b128 v[120:123], v96 offset:4672
	s_waitcnt lgkmcnt(8)
	v_mfma_f32_16x16x32_bf16 v[188:191], v[136:139], v[68:71], v[188:191]
	ds_read_b128 v[124:127], v89 offset:128
	ds_read_b128 v[128:131], v90 offset:128
	ds_read_b128 v[132:135], v96 offset:6912
	s_waitcnt lgkmcnt(8)
	v_mfma_f32_16x16x32_bf16 v[192:195], v[148:151], v[72:75], 0
	ds_read_b128 v[136:139], v96 offset:6976
	s_waitcnt lgkmcnt(8)
	v_mfma_f32_16x16x32_bf16 v[192:195], v[152:155], v[68:71], v[192:195]
	v_cvt_pk_bf16_f32 v170, v160, v161
	v_cvt_pk_bf16_f32 v171, v162, v163
	global_store_dwordx2 v[18:19], v[170:171], off offset:96
	ds_read_b128 v[148:151], v89 offset:192
	ds_read_b128 v[152:155], v90 offset:192
	s_waitcnt lgkmcnt(7)
	v_mfma_f32_16x16x32_bf16 v[196:199], v[116:119], v[72:75], 0
	s_waitcnt lgkmcnt(6)
	v_mfma_f32_16x16x32_bf16 v[196:199], v[120:123], v[68:71], v[196:199]
	v_pk_mul_f32 v[146:147], v[190:191], v[146:147]
	v_pk_mul_f32 v[144:145], v[188:189], v[144:145]
	v_pk_fma_f32 v[54:55], v[54:55], v[142:143], v[146:147]
	v_pk_fma_f32 v[52:53], v[52:53], v[140:141], v[144:145]
	s_waitcnt lgkmcnt(3)
	v_mfma_f32_16x16x32_bf16 v[188:191], v[132:135], v[72:75], 0
	s_waitcnt lgkmcnt(2)
	v_mfma_f32_16x16x32_bf16 v[188:191], v[136:139], v[68:71], v[188:191]
	v_pk_mul_f32 v[114:115], v[194:195], v[114:115]
	v_pk_mul_f32 v[112:113], v[192:193], v[112:113]
	v_pk_fma_f32 v[58:59], v[58:59], v[110:111], v[114:115]
	v_pk_fma_f32 v[56:57], v[56:57], v[108:109], v[112:113]
	v_pk_mul_f32 v[130:131], v[198:199], v[130:131]
	v_pk_mul_f32 v[128:129], v[196:197], v[128:129]
	v_pk_fma_f32 v[62:63], v[62:63], v[126:127], v[130:131]
	v_pk_fma_f32 v[60:61], v[60:61], v[124:125], v[128:129]
	s_waitcnt lgkmcnt(0)
	v_pk_mul_f32 v[154:155], v[190:191], v[154:155]
	v_pk_mul_f32 v[152:153], v[188:189], v[152:153]
	v_pk_fma_f32 v[66:67], v[66:67], v[150:151], v[154:155]
	v_pk_fma_f32 v[64:65], v[64:65], v[148:149], v[152:153]
	s_add_i32 s8, s17, 1
	s_cmp_gt_u32 s8, 62
	s_cbranch_scc1 .LBB0_993
.LBB0_995:
	v_mov_b32_e32 v70, v86
	s_mov_b32 s0, 0xffffffe
	v_ashrrev_i32_e32 v16, 31, v70
	v_lshrrev_b32_e32 v16, 29, v16
	v_add_u32_e32 v18, v70, v16
	v_lshrrev_b32_e32 v16, 3, v18
	v_and_b32_e32 v18, 0xffffff8, v18
	v_sub_u32_e32 v18, v70, v18
	v_mul_lo_u32 v19, v16, s63
	v_lshlrev_b32_e32 v16, 4, v70
	v_lshlrev_b32_e32 v18, 4, v18
	v_and_b32_e32 v69, 0x70, v16
	v_add_u32_e32 v73, 0x200, v70
	v_add3_u32 v18, 0, v19, v18
	v_ashrrev_i32_e32 v68, 3, v70
	v_bfe_u32 v71, v70, 3, 1
	v_lshrrev_b32_e32 v73, 3, v73
	s_waitcnt vmcnt(13)
	ds_write_b128 v18, v[32:35]
	v_add_u32_e32 v18, 0, v69
	v_and_or_b32 v72, v68, s0, v71
	v_and_or_b32 v71, v73, s0, v71
	v_mad_u64_u32 v[68:69], s[0:1], v68, s63, v[18:19]
	ds_write_b128 v68, v[36:39] offset:17408
	ds_write_b128 v68, v[40:43] offset:26624
	v_mad_u64_u32 v[68:69], s[0:1], v72, s63, v[18:19]
	v_mad_u64_u32 v[18:19], s[0:1], v71, s63, v[18:19]
	v_cmp_gt_i32_e32 vcc, 48, v70
	ds_write_b128 v68, v[44:47] offset:45056
	ds_write_b128 v18, v[48:51] offset:45056
	s_and_saveexec_b64 s[0:1], vcc
	v_add_u32_e32 v16, 0, v16
	ds_write_b128 v16, v[28:31] offset:63488
	s_or_b64 exec, exec, s[0:1]
	s_cmp_gt_u32 s8, 60
	s_cbranch_scc1 .LBB0_982

.Lgla_done:
	s_cmp_gt_u32 s50, 35
	s_cbranch_scc1 .LBB0_1000
	s_sub_i32 s96, s50, 32
	s_branch .Llru_entry

.LBB0_1020:
	v_mov_b32_e32 v159, v158
	s_mov_b32 s0, 0xffffffe
	v_add_u32_e32 v162, 0x100, v159
	v_add_u32_e32 v164, 0x200, v159
	v_add_u32_e32 v166, 0x300, v159
	v_ashrrev_i32_e32 v169, 3, v159
	v_ashrrev_i32_e32 v170, 3, v162
	v_lshrrev_b32_e32 v163, 4, v162
	v_lshrrev_b32_e32 v165, 4, v164
	v_lshrrev_b32_e32 v167, 4, v166
	v_bfe_u32 v162, v159, 3, 1
	v_lshrrev_b32_e32 v164, 3, v164
	v_lshrrev_b32_e32 v166, 3, v166
	v_add_u32_e32 v173, s2, v169
	v_add_u32_e32 v174, s2, v170
	v_and_or_b32 v171, v169, s0, v162
	v_and_or_b32 v172, v170, s0, v162
	v_and_or_b32 v164, v164, s0, v162
	v_and_or_b32 v166, v166, s0, v162
	v_and_or_b32 v173, v173, s0, v162
	v_and_or_b32 v174, v174, s0, v162
	s_andn2_b32 s0, 1, s6
	v_lshlrev_b32_e32 v16, 4, v159
	v_lshrrev_b32_e32 v161, 4, v159
	s_mul_i32 s0, s0, 0x10400
	v_and_b32_e32 v160, 0xf0, v16
	v_mul_lo_u32 v161, v161, s25
	s_add_i32 s7, s0, 0
	v_mul_lo_u32 v163, v163, s25
	v_add3_u32 v161, s7, v161, v160
	v_mul_lo_u32 v165, v165, s25
	v_mul_lo_u32 v167, v167, s25
	s_waitcnt vmcnt(24)
	ds_write_b128 v161, v[4:7]
	v_add3_u32 v161, s7, v163, v160
	v_and_b32_e32 v168, 0x70, v16
	ds_write_b128 v161, v[8:11]
	v_add3_u32 v161, s7, v165, v160
	v_add3_u32 v160, s7, v167, v160
	ds_write_b128 v161, v[12:15]
	ds_write_b128 v160, v[18:21]
	v_add_u32_e32 v160, s7, v168
	v_mad_u64_u32 v[162:163], s[0:1], v169, s63, v[160:161]
	ds_write_b128 v162, v[22:25] offset:17408
	v_mad_u64_u32 v[162:163], s[0:1], v170, s63, v[160:161]
	ds_write_b128 v162, v[26:29] offset:17408
	v_mad_u64_u32 v[162:163], s[0:1], v171, s63, v[160:161]
	ds_write_b128 v162, v[30:33] offset:26624
	v_mad_u64_u32 v[162:163], s[0:1], v172, s63, v[160:161]
	ds_write_b128 v162, v[34:37] offset:26624
	v_mad_u64_u32 v[162:163], s[0:1], v164, s63, v[160:161]
	ds_write_b128 v162, v[38:41] offset:26624
	v_mad_u64_u32 v[162:163], s[0:1], v166, s63, v[160:161]
	ds_write_b128 v162, v[42:45] offset:26624
	v_mad_u64_u32 v[162:163], s[0:1], v173, s63, v[160:161]
	v_mad_u64_u32 v[160:161], s[0:1], v174, s63, v[160:161]
	s_movk_i32 s0, 0x60
	s_nop 0
	v_cmp_gt_i32_e32 vcc, s0, v159
	ds_write_b128 v162, v[58:61] offset:45056
	ds_write_b128 v160, v[62:65] offset:45056
	s_and_saveexec_b64 s[0:1], vcc
	v_add_u32_e32 v16, s7, v16
	ds_write_b128 v16, v[0:3] offset:63488
	s_or_b64 exec, exec, s[0:1]
	s_cmp_gt_u32 s6, 59
	s_cselect_b64 s[0:1], -1, 0
	s_and_b64 vcc, exec, s[0:1]
	s_cbranch_vccnz .LBB0_1026
	v_mov_b32_e32 v159, v158
	v_mov_b32_e32 v31, v17
	v_lshlrev_b32_e32 v5, 3, v159
	v_add_u32_e32 v10, 0x100, v159
	v_add_u32_e32 v12, 0x200, v159
	v_add_u32_e32 v14, 0x300, v159
	v_and_b32_e32 v7, 0x78, v5
	v_ashrrev_i32_e32 v8, 4, v159
	v_ashrrev_i32_e32 v11, 4, v10
	v_lshrrev_b32_e32 v12, 4, v12
	v_lshrrev_b32_e32 v14, 4, v14
	v_or_b32_e32 v6, s12, v7
	v_mul_lo_u32 v9, v8, s60
	v_mul_lo_u32 v13, v11, s60
	v_mul_lo_u32 v15, v12, s60
	v_mul_lo_u32 v18, v14, s60
	v_add_u32_e32 v16, v6, v9
	v_add_u32_e32 v4, v13, v6
	v_add_u32_e32 v12, v15, v6
	v_add_u32_e32 v14, v18, v6
	v_and_or_b32 v6, v5, 56, s17
	v_lshrrev_b32_e32 v5, 3, v159
	v_mad_u64_u32 v[22:23], s[4:5], v5, s60, v[6:7]
	v_lshrrev_b32_e32 v5, 3, v10
	v_mad_u64_u32 v[24:25], s[4:5], v5, s60, v[6:7]
	v_or_b32_e32 v5, s13, v7
	v_add_u32_e32 v30, v5, v9
	v_add_u32_e32 v32, v13, v5
	v_add_u32_e32 v38, v15, v5
	v_add_u32_e32 v40, v18, v5
	v_or_b32_e32 v6, s16, v7
	v_add_u32_e32 v5, s20, v8
	v_mad_u64_u32 v[58:59], s[4:5], v5, s60, v[6:7]
	v_add_u32_e32 v5, s20, v11
	v_mad_u64_u32 v[60:61], s[4:5], v5, s60, v[6:7]
	s_add_u32 s4, s82, s9
	s_addc_u32 s5, s83, s8
	v_lshl_add_u64 v[6:7], v[16:17], 1, s[4:5]
	v_add_co_u32_e32 v6, vcc, s35, v6
	v_mov_b32_e32 v5, v17
	s_nop 0
	v_addc_co_u32_e32 v7, vcc, 0, v7, vcc
	v_lshl_add_u64 v[4:5], v[4:5], 1, s[4:5]
	v_add_co_u32_e32 v8, vcc, s35, v4
	v_mov_b32_e32 v13, v17
	s_nop 0
	v_addc_co_u32_e32 v9, vcc, 0, v5, vcc
	v_lshl_add_u64 v[12:13], v[12:13], 1, s[4:5]
	v_add_co_u32_e32 v12, vcc, s35, v12
	v_mov_b32_e32 v15, v17
	s_nop 0
	v_addc_co_u32_e32 v13, vcc, 0, v13, vcc
	v_lshl_add_u64 v[14:15], v[14:15], 1, s[4:5]
	v_add_co_u32_e32 v18, vcc, s35, v14
	v_mov_b32_e32 v23, v17
	s_nop 0
	v_addc_co_u32_e32 v19, vcc, 0, v15, vcc
	v_lshl_add_u64 v[22:23], v[22:23], 1, s[4:5]
	v_add_co_u32_e32 v22, vcc, s35, v22
	v_mov_b32_e32 v25, v17
	s_nop 0
	v_addc_co_u32_e32 v23, vcc, 0, v23, vcc
	v_lshl_add_u64 v[24:25], v[24:25], 1, s[4:5]
	v_add_co_u32_e32 v26, vcc, s35, v24
	v_lshl_add_u64 v[30:31], v[30:31], 1, s[4:5]
	s_nop 0
	v_addc_co_u32_e32 v27, vcc, 0, v25, vcc
	v_add_co_u32_e32 v30, vcc, s35, v30
	v_mov_b32_e32 v33, v17
	s_nop 0
	v_addc_co_u32_e32 v31, vcc, 0, v31, vcc
	v_lshl_add_u64 v[32:33], v[32:33], 1, s[4:5]
	v_add_co_u32_e32 v34, vcc, s35, v32
	v_mov_b32_e32 v39, v17
	s_nop 0
	v_addc_co_u32_e32 v35, vcc, 0, v33, vcc
	v_lshl_add_u64 v[38:39], v[38:39], 1, s[4:5]
	v_add_co_u32_e32 v38, vcc, s35, v38
	v_mov_b32_e32 v41, v17
	s_nop 0
	v_addc_co_u32_e32 v39, vcc, 0, v39, vcc
	v_lshl_add_u64 v[40:41], v[40:41], 1, s[4:5]
	v_add_co_u32_e32 v42, vcc, s35, v40
	v_mov_b32_e32 v59, v17
	s_nop 0
	v_addc_co_u32_e32 v43, vcc, 0, v41, vcc
	v_lshl_add_u64 v[58:59], v[58:59], 1, s[4:5]
	v_add_co_u32_e32 v58, vcc, 0x380000, v58
	v_mov_b32_e32 v61, v17
	s_nop 0
	v_addc_co_u32_e32 v59, vcc, 0, v59, vcc
	v_lshl_add_u64 v[60:61], v[60:61], 1, s[4:5]
	v_add_co_u32_e32 v62, vcc, 0x380000, v60
	global_load_dwordx4 v[4:7], v[6:7], off
	s_nop 0
	global_load_dwordx4 v[8:11], v[8:9], off
	v_addc_co_u32_e32 v63, vcc, 0, v61, vcc
	global_load_dwordx4 v[12:15], v[12:13], off
	s_nop 0
	global_load_dwordx4 v[18:21], v[18:19], off
	s_nop 0
	global_load_dwordx4 v[22:25], v[22:23], off
	s_nop 0
	global_load_dwordx4 v[26:29], v[26:27], off
	s_nop 0
	global_load_dwordx4 v[30:33], v[30:31], off
	s_nop 0
	global_load_dwordx4 v[34:37], v[34:35], off
	s_nop 0
	global_load_dwordx4 v[38:41], v[38:39], off
	s_nop 0
	global_load_dwordx4 v[42:45], v[42:43], off
	s_nop 0
	global_load_dwordx4 v[58:61], v[58:59], off
	s_nop 0
	global_load_dwordx4 v[62:65], v[62:63], off
	s_movk_i32 s4, 0x60
	v_cmp_gt_i32_e32 vcc, s4, v159
	s_and_saveexec_b64 s[4:5], vcc
	s_cbranch_execz .LBB0_1025
	v_lshlrev_b32_e32 v0, 2, v159
	s_add_u32 s22, s82, s11
	v_ashrrev_i32_e32 v1, 31, v0
	s_addc_u32 s23, s83, s10
	v_lshl_add_u64 v[0:1], v[0:1], 2, s[22:23]
	v_add_co_u32_e32 v0, vcc, 0x1f641000, v0
	s_nop 1
	v_addc_co_u32_e32 v1, vcc, 0, v1, vcc
	global_load_dwordx4 v[0:3], v[0:1], off offset:2048

.LBB0_1026:
	v_mov_b32_e32 v159, v158
	s_waitcnt lgkmcnt(0)
	s_barrier
	s_cmp_lt_u32 s6, 60
	s_cbranch_scc1 .Lhl_b_w24
	s_waitcnt vmcnt(0)
.Lhl_b_w24:
	s_waitcnt vmcnt(24)
	s_mov_b32 s4, 0xffffffe
	v_add_u32_e32 v162, 0x100, v159
	v_add_u32_e32 v164, 0x200, v159
	v_add_u32_e32 v166, 0x300, v159
	v_ashrrev_i32_e32 v169, 3, v159
	v_ashrrev_i32_e32 v170, 3, v162
	v_lshrrev_b32_e32 v163, 4, v162
	v_lshrrev_b32_e32 v165, 4, v164
	v_lshrrev_b32_e32 v167, 4, v166
	v_bfe_u32 v162, v159, 3, 1
	v_lshrrev_b32_e32 v164, 3, v164
	v_lshrrev_b32_e32 v166, 3, v166
	v_add_u32_e32 v173, s2, v169
	v_add_u32_e32 v174, s2, v170
	s_bitcmp1_b32 s6, 0
	v_lshlrev_b32_e32 v16, 4, v159
	v_lshrrev_b32_e32 v161, 4, v159
	v_and_or_b32 v171, v169, s4, v162
	v_and_or_b32 v172, v170, s4, v162
	v_and_or_b32 v164, v164, s4, v162
	v_and_or_b32 v166, v166, s4, v162
	v_and_or_b32 v173, v173, s4, v162
	v_and_or_b32 v174, v174, s4, v162
	s_cselect_b32 s4, 0x10400, 0
	v_and_b32_e32 v160, 0xf0, v16
	v_mul_lo_u32 v161, v161, s25
	s_add_i32 s21, s4, 0
	v_mul_lo_u32 v163, v163, s25
	v_add3_u32 v161, s21, v161, v160
	v_mul_lo_u32 v165, v165, s25
	v_mul_lo_u32 v167, v167, s25
	ds_write_b128 v161, v[46:49]
	v_add3_u32 v161, s21, v163, v160
	v_and_b32_e32 v168, 0x70, v16
	ds_write_b128 v161, v[50:53]
	v_add3_u32 v161, s21, v165, v160
	v_add3_u32 v160, s21, v167, v160
	ds_write_b128 v161, v[66:69]
	ds_write_b128 v160, v[70:73]
	v_add_u32_e32 v160, s21, v168
	v_mad_u64_u32 v[162:163], s[4:5], v169, s63, v[160:161]
	ds_write_b128 v162, v[74:77] offset:17408
	v_mad_u64_u32 v[162:163], s[4:5], v170, s63, v[160:161]
	ds_write_b128 v162, v[78:81] offset:17408
	v_mad_u64_u32 v[162:163], s[4:5], v171, s63, v[160:161]
	ds_write_b128 v162, v[82:85] offset:26624
	v_mad_u64_u32 v[162:163], s[4:5], v172, s63, v[160:161]
	ds_write_b128 v162, v[86:89] offset:26624
	v_mad_u64_u32 v[162:163], s[4:5], v164, s63, v[160:161]
	ds_write_b128 v162, v[90:93] offset:26624
	v_mad_u64_u32 v[162:163], s[4:5], v166, s63, v[160:161]
	ds_write_b128 v162, v[94:97] offset:26624
	v_mad_u64_u32 v[162:163], s[4:5], v173, s63, v[160:161]
	v_mad_u64_u32 v[160:161], s[4:5], v174, s63, v[160:161]
	s_movk_i32 s4, 0x60
	s_nop 0
	v_cmp_gt_i32_e32 vcc, s4, v159
	ds_write_b128 v162, v[110:113] offset:45056
	ds_write_b128 v160, v[118:121] offset:45056
	s_and_saveexec_b64 s[4:5], vcc
	v_add_u32_e32 v16, s21, v16
	ds_write_b128 v16, v[54:57] offset:63488
	s_or_b64 exec, exec, s[4:5]
	s_cmp_gt_u32 s6, 58
	s_cbranch_scc1 .LBB0_1032
	v_mov_b32_e32 v159, v158
	s_mov_b32 s21, 0x460000
	v_lshlrev_b32_e32 v47, 3, v159
	v_add_u32_e32 v52, 0x100, v159
	v_add_u32_e32 v66, 0x200, v159
	v_add_u32_e32 v68, 0x300, v159
	v_and_b32_e32 v49, 0x78, v47
	v_ashrrev_i32_e32 v50, 4, v159
	v_ashrrev_i32_e32 v53, 4, v52
	v_lshrrev_b32_e32 v66, 4, v66
	v_lshrrev_b32_e32 v68, 4, v68
	v_or_b32_e32 v48, s12, v49
	v_mul_lo_u32 v51, v50, s60
	v_mul_lo_u32 v67, v53, s60
	v_mul_lo_u32 v69, v66, s60
	v_mul_lo_u32 v70, v68, s60
	v_add_u32_e32 v16, v48, v51
	v_add_u32_e32 v46, v67, v48
	v_add_u32_e32 v66, v69, v48
	v_add_u32_e32 v68, v70, v48
	v_and_or_b32 v48, v47, 56, s17
	v_lshrrev_b32_e32 v47, 3, v159
	v_mad_u64_u32 v[74:75], s[4:5], v47, s60, v[48:49]
	v_lshrrev_b32_e32 v47, 3, v52
	v_mad_u64_u32 v[76:77], s[4:5], v47, s60, v[48:49]
	v_or_b32_e32 v47, s13, v49
	v_add_u32_e32 v82, v47, v51
	v_add_u32_e32 v84, v67, v47
	v_add_u32_e32 v90, v69, v47
	v_add_u32_e32 v92, v70, v47
	v_or_b32_e32 v48, s16, v49
	v_add_u32_e32 v47, s20, v50
	v_mad_u64_u32 v[110:111], s[4:5], v47, s60, v[48:49]
	v_add_u32_e32 v47, s20, v53
	v_mad_u64_u32 v[112:113], s[4:5], v47, s60, v[48:49]
	s_add_u32 s4, s82, s9
	s_addc_u32 s5, s83, s8
	v_lshl_add_u64 v[48:49], v[16:17], 1, s[4:5]
	v_add_co_u32_e32 v48, vcc, s21, v48
	v_mov_b32_e32 v47, v17
	s_nop 0
	v_addc_co_u32_e32 v49, vcc, 0, v49, vcc
	v_lshl_add_u64 v[46:47], v[46:47], 1, s[4:5]
	v_add_co_u32_e32 v50, vcc, s21, v46
	v_mov_b32_e32 v67, v17
	s_nop 0
	v_addc_co_u32_e32 v51, vcc, 0, v47, vcc
	v_lshl_add_u64 v[66:67], v[66:67], 1, s[4:5]
	v_add_co_u32_e32 v66, vcc, s21, v66
	v_mov_b32_e32 v69, v17
	s_nop 0
	v_addc_co_u32_e32 v67, vcc, 0, v67, vcc
	v_lshl_add_u64 v[68:69], v[68:69], 1, s[4:5]
	v_add_co_u32_e32 v70, vcc, s21, v68
	v_mov_b32_e32 v75, v17
	s_nop 0
	v_addc_co_u32_e32 v71, vcc, 0, v69, vcc
	v_lshl_add_u64 v[74:75], v[74:75], 1, s[4:5]
	v_add_co_u32_e32 v74, vcc, s21, v74
	v_mov_b32_e32 v77, v17
	s_nop 0
	v_addc_co_u32_e32 v75, vcc, 0, v75, vcc
	v_lshl_add_u64 v[76:77], v[76:77], 1, s[4:5]
	v_add_co_u32_e32 v78, vcc, s21, v76
	v_mov_b32_e32 v83, v17
	s_nop 0
	v_addc_co_u32_e32 v79, vcc, 0, v77, vcc
	v_lshl_add_u64 v[82:83], v[82:83], 1, s[4:5]
	v_add_co_u32_e32 v82, vcc, s21, v82
	v_mov_b32_e32 v85, v17
	s_nop 0
	v_addc_co_u32_e32 v83, vcc, 0, v83, vcc
	v_lshl_add_u64 v[84:85], v[84:85], 1, s[4:5]
	v_add_co_u32_e32 v86, vcc, s21, v84
	v_mov_b32_e32 v91, v17
	s_nop 0
	v_addc_co_u32_e32 v87, vcc, 0, v85, vcc
	v_lshl_add_u64 v[90:91], v[90:91], 1, s[4:5]
	v_add_co_u32_e32 v90, vcc, s21, v90
	v_mov_b32_e32 v93, v17
	s_nop 0
	v_addc_co_u32_e32 v91, vcc, 0, v91, vcc
	v_lshl_add_u64 v[92:93], v[92:93], 1, s[4:5]
	v_add_co_u32_e32 v94, vcc, s21, v92
	v_mov_b32_e32 v111, v17
	s_nop 0
	v_addc_co_u32_e32 v95, vcc, 0, v93, vcc
	v_lshl_add_u64 v[110:111], v[110:111], 1, s[4:5]
	v_add_co_u32_e32 v110, vcc, 0x460000, v110
	v_mov_b32_e32 v113, v17
	s_nop 0
	v_addc_co_u32_e32 v111, vcc, 0, v111, vcc
	v_lshl_add_u64 v[112:113], v[112:113], 1, s[4:5]
	v_add_co_u32_e32 v118, vcc, 0x460000, v112
	global_load_dwordx4 v[46:49], v[48:49], off
	s_nop 0
	global_load_dwordx4 v[50:53], v[50:51], off
	v_addc_co_u32_e32 v119, vcc, 0, v113, vcc
	global_load_dwordx4 v[66:69], v[66:67], off
	s_nop 0
	global_load_dwordx4 v[70:73], v[70:71], off
	s_nop 0
	global_load_dwordx4 v[74:77], v[74:75], off
	s_nop 0
	global_load_dwordx4 v[78:81], v[78:79], off
	s_nop 0
	global_load_dwordx4 v[82:85], v[82:83], off
	s_nop 0
	global_load_dwordx4 v[86:89], v[86:87], off
	s_nop 0
	global_load_dwordx4 v[90:93], v[90:91], off
	s_nop 0
	global_load_dwordx4 v[94:97], v[94:95], off
	s_nop 0
	global_load_dwordx4 v[110:113], v[110:111], off
	s_nop 0
	global_load_dwordx4 v[118:121], v[118:119], off
	s_movk_i32 s4, 0x60
	v_cmp_gt_i32_e32 vcc, s4, v159
	s_and_saveexec_b64 s[4:5], vcc
	s_cbranch_execz .LBB0_1031
	v_lshlrev_b32_e32 v54, 2, v159
	s_add_u32 s22, s82, s11
	v_ashrrev_i32_e32 v55, 31, v54
	s_addc_u32 s23, s83, s10
	v_lshl_add_u64 v[54:55], v[54:55], 2, s[22:23]
	v_add_co_u32_e32 v54, vcc, 0x1f641000, v54
	s_nop 1
	v_addc_co_u32_e32 v55, vcc, 0, v55, vcc
	global_load_dwordx4 v[54:57], v[54:55], off offset:3584

.Lhl_c_w24:
	s_waitcnt vmcnt(24)
	s_mov_b32 s4, 0xffffffe
	v_lshlrev_b32_e32 v16, 4, v159
	v_lshrrev_b32_e32 v161, 4, v159
	v_add_u32_e32 v162, 0x100, v159
	v_and_b32_e32 v160, 0xf0, v16
	v_mul_lo_u32 v161, v161, s25
	v_lshrrev_b32_e32 v163, 4, v162
	v_add_u32_e32 v164, 0x200, v159
	v_add_u32_e32 v166, 0x300, v159
	v_mul_lo_u32 v163, v163, s25
	v_lshrrev_b32_e32 v165, 4, v164
	v_lshrrev_b32_e32 v167, 4, v166
	v_add3_u32 v161, s7, v161, v160
	v_mul_lo_u32 v165, v165, s25
	v_mul_lo_u32 v167, v167, s25
	ds_write_b128 v161, v[98:101]
	v_add3_u32 v161, s7, v163, v160
	v_and_b32_e32 v168, 0x70, v16
	v_ashrrev_i32_e32 v169, 3, v159
	v_ashrrev_i32_e32 v170, 3, v162
	ds_write_b128 v161, v[102:105]
	v_add3_u32 v161, s7, v165, v160
	v_add3_u32 v160, s7, v167, v160
	v_bfe_u32 v162, v159, 3, 1
	v_lshrrev_b32_e32 v164, 3, v164
	v_lshrrev_b32_e32 v166, 3, v166
	v_add_u32_e32 v173, s2, v169
	v_add_u32_e32 v174, s2, v170
	ds_write_b128 v161, v[114:117]
	ds_write_b128 v160, v[122:125]
	v_add_u32_e32 v160, s7, v168
	v_and_or_b32 v171, v169, s4, v162
	v_and_or_b32 v172, v170, s4, v162
	v_and_or_b32 v164, v164, s4, v162
	v_and_or_b32 v166, v166, s4, v162
	v_and_or_b32 v173, v173, s4, v162
	v_and_or_b32 v174, v174, s4, v162
	v_mad_u64_u32 v[162:163], s[4:5], v169, s63, v[160:161]
	ds_write_b128 v162, v[126:129] offset:17408
	v_mad_u64_u32 v[162:163], s[4:5], v170, s63, v[160:161]
	ds_write_b128 v162, v[130:133] offset:17408
	v_mad_u64_u32 v[162:163], s[4:5], v171, s63, v[160:161]
	ds_write_b128 v162, v[134:137] offset:26624
	v_mad_u64_u32 v[162:163], s[4:5], v172, s63, v[160:161]
	ds_write_b128 v162, v[138:141] offset:26624
	v_mad_u64_u32 v[162:163], s[4:5], v164, s63, v[160:161]
	ds_write_b128 v162, v[142:145] offset:26624
	v_mad_u64_u32 v[162:163], s[4:5], v166, s63, v[160:161]
	ds_write_b128 v162, v[146:149] offset:26624
	v_mad_u64_u32 v[162:163], s[4:5], v173, s63, v[160:161]
	v_mad_u64_u32 v[160:161], s[4:5], v174, s63, v[160:161]
	s_movk_i32 s4, 0x60
	s_nop 0
	v_cmp_gt_i32_e32 vcc, s4, v159
	ds_write_b128 v162, v[150:153] offset:45056
	ds_write_b128 v160, v[154:157] offset:45056
	s_and_saveexec_b64 s[4:5], vcc
	v_add_u32_e32 v16, s7, v16
	ds_write_b128 v16, v[106:109] offset:63488
	s_or_b64 exec, exec, s[4:5]
	s_cmp_gt_u32 s6, 57
	s_cbranch_scc1 .LBB0_1019
	v_mov_b32_e32 v159, v158
	s_mov_b32 s7, 0x540000
	v_lshlrev_b32_e32 v99, 3, v159
	v_add_u32_e32 v104, 0x100, v159
	v_add_u32_e32 v114, 0x200, v159
	v_add_u32_e32 v116, 0x300, v159
	v_and_b32_e32 v101, 0x78, v99
	v_ashrrev_i32_e32 v102, 4, v159
	v_ashrrev_i32_e32 v105, 4, v104
	v_lshrrev_b32_e32 v114, 4, v114
	v_lshrrev_b32_e32 v116, 4, v116
	v_or_b32_e32 v100, s12, v101
	v_mul_lo_u32 v103, v102, s60
	v_mul_lo_u32 v115, v105, s60
	v_mul_lo_u32 v117, v114, s60
	v_mul_lo_u32 v122, v116, s60
	v_add_u32_e32 v16, v100, v103
	v_add_u32_e32 v98, v115, v100
	v_add_u32_e32 v114, v117, v100
	v_add_u32_e32 v116, v122, v100
	v_and_or_b32 v100, v99, 56, s17
	v_lshrrev_b32_e32 v99, 3, v159
	v_mad_u64_u32 v[126:127], s[4:5], v99, s60, v[100:101]
	v_lshrrev_b32_e32 v99, 3, v104
	v_mad_u64_u32 v[128:129], s[4:5], v99, s60, v[100:101]
	v_or_b32_e32 v99, s13, v101
	v_add_u32_e32 v134, v99, v103
	v_add_u32_e32 v136, v115, v99
	v_add_u32_e32 v142, v117, v99
	v_add_u32_e32 v144, v122, v99
	v_or_b32_e32 v100, s16, v101
	v_add_u32_e32 v99, s20, v102
	v_mad_u64_u32 v[150:151], s[4:5], v99, s60, v[100:101]
	v_add_u32_e32 v99, s20, v105
	v_mad_u64_u32 v[152:153], s[4:5], v99, s60, v[100:101]
	s_add_u32 s4, s82, s9
	s_addc_u32 s5, s83, s8
	v_lshl_add_u64 v[100:101], v[16:17], 1, s[4:5]
	v_add_co_u32_e32 v100, vcc, s7, v100
	v_mov_b32_e32 v99, v17
	s_nop 0
	v_addc_co_u32_e32 v101, vcc, 0, v101, vcc
	v_lshl_add_u64 v[98:99], v[98:99], 1, s[4:5]
	v_add_co_u32_e32 v102, vcc, s7, v98
	v_mov_b32_e32 v115, v17
	s_nop 0
	v_addc_co_u32_e32 v103, vcc, 0, v99, vcc
	v_lshl_add_u64 v[114:115], v[114:115], 1, s[4:5]
	v_add_co_u32_e32 v114, vcc, s7, v114
	v_mov_b32_e32 v117, v17
	s_nop 0
	v_addc_co_u32_e32 v115, vcc, 0, v115, vcc
	v_lshl_add_u64 v[116:117], v[116:117], 1, s[4:5]
	v_add_co_u32_e32 v122, vcc, s7, v116
	v_mov_b32_e32 v127, v17
	s_nop 0
	v_addc_co_u32_e32 v123, vcc, 0, v117, vcc
	v_lshl_add_u64 v[126:127], v[126:127], 1, s[4:5]
	v_add_co_u32_e32 v126, vcc, s7, v126
	v_mov_b32_e32 v129, v17
	s_nop 0
	v_addc_co_u32_e32 v127, vcc, 0, v127, vcc
	v_lshl_add_u64 v[128:129], v[128:129], 1, s[4:5]
	v_add_co_u32_e32 v130, vcc, s7, v128
	v_mov_b32_e32 v135, v17
	s_nop 0
	v_addc_co_u32_e32 v131, vcc, 0, v129, vcc
	v_lshl_add_u64 v[134:135], v[134:135], 1, s[4:5]
	v_add_co_u32_e32 v134, vcc, s7, v134
	v_mov_b32_e32 v137, v17
	s_nop 0
	v_addc_co_u32_e32 v135, vcc, 0, v135, vcc
	v_lshl_add_u64 v[136:137], v[136:137], 1, s[4:5]
	v_add_co_u32_e32 v138, vcc, s7, v136
	v_mov_b32_e32 v143, v17
	s_nop 0
	v_addc_co_u32_e32 v139, vcc, 0, v137, vcc
	v_lshl_add_u64 v[142:143], v[142:143], 1, s[4:5]
	v_add_co_u32_e32 v142, vcc, s7, v142
	v_mov_b32_e32 v145, v17
	s_nop 0
	v_addc_co_u32_e32 v143, vcc, 0, v143, vcc
	v_lshl_add_u64 v[144:145], v[144:145], 1, s[4:5]
	v_add_co_u32_e32 v146, vcc, s7, v144
	v_mov_b32_e32 v151, v17
	s_nop 0
	v_addc_co_u32_e32 v147, vcc, 0, v145, vcc
	v_lshl_add_u64 v[150:151], v[150:151], 1, s[4:5]
	v_add_co_u32_e32 v150, vcc, 0x540000, v150
	v_mov_b32_e32 v153, v17
	s_nop 0
	v_addc_co_u32_e32 v151, vcc, 0, v151, vcc
	v_lshl_add_u64 v[152:153], v[152:153], 1, s[4:5]
	v_add_co_u32_e32 v154, vcc, 0x540000, v152
	global_load_dwordx4 v[98:101], v[100:101], off
	s_nop 0
	global_load_dwordx4 v[102:105], v[102:103], off
	v_addc_co_u32_e32 v155, vcc, 0, v153, vcc
	global_load_dwordx4 v[114:117], v[114:115], off
	s_nop 0
	global_load_dwordx4 v[122:125], v[122:123], off
	s_nop 0
	global_load_dwordx4 v[126:129], v[126:127], off
	s_nop 0
	global_load_dwordx4 v[130:133], v[130:131], off
	s_nop 0
	global_load_dwordx4 v[134:137], v[134:135], off
	s_nop 0
	global_load_dwordx4 v[138:141], v[138:139], off
	s_nop 0
	global_load_dwordx4 v[142:145], v[142:143], off
	s_nop 0
	global_load_dwordx4 v[146:149], v[146:147], off
	s_nop 0
	global_load_dwordx4 v[150:153], v[150:151], off
	s_nop 0
	global_load_dwordx4 v[154:157], v[154:155], off
	s_movk_i32 s4, 0x60
	v_cmp_gt_i32_e32 vcc, s4, v159
	s_and_saveexec_b64 s[4:5], vcc
	s_cbranch_execz .LBB0_1018
	v_lshlrev_b32_e32 v106, 2, v159
	s_add_u32 s22, s82, s11
	v_ashrrev_i32_e32 v107, 31, v106
	s_addc_u32 s23, s83, s10
	v_lshl_add_u64 v[106:107], v[106:107], 2, s[22:23]
	v_add_co_u32_e32 v106, vcc, 0x1f642000, v106
	s_nop 1
	v_addc_co_u32_e32 v107, vcc, 0, v107, vcc
	global_load_dwordx4 v[106:109], v[106:107], off offset:1024
	s_branch .LBB0_1018

.LBB0_1159:
	v_cndmask_b32_e64 v1, 0, 1, s[4:5]
	v_cmp_ne_u32_e64 s[0:1], 1, v1
	s_andn2_b64 vcc, exec, s[4:5]
	s_cbranch_vccnz .LBB0_1307
	v_bfe_i32 v2, v0, 27, 1
	v_lshlrev_b32_e32 v5, 4, v0
	v_lshrrev_b32_e32 v2, 22, v2
	v_add_u32_e32 v2, v5, v2
	v_and_b32_e32 v2, 0xfffffc00, v2
	v_sub_u32_e32 v2, v5, v2
	v_lshrrev_b32_e32 v3, 4, v2
	v_ashrrev_i32_e32 v1, 31, v0
	v_bitop3_b32 v4, v3, v2, 32 bitop3:0x6c
	v_ashrrev_i32_e32 v2, 31, v2
	v_lshrrev_b32_e32 v1, 26, v1
	v_lshrrev_b32_e32 v2, 26, v2
	v_add_u32_e32 v1, v0, v1
	v_add_u32_e32 v2, v4, v2
	v_ashrrev_i32_e32 v1, 6, v1
	v_ashrrev_i32_e32 v2, 6, v2
	v_lshlrev_b32_e32 v3, 3, v1
	v_mul_i32_i24_e32 v7, 64, v2
	v_and_b32_e32 v3, -16, v3
	v_sub_u32_e32 v4, v4, v7
	v_add_u32_e32 v6, v2, v3
	v_lshlrev_b32_e32 v3, 5, v1
	v_ashrrev_i16_sdwa v4, v237, sext(v4) dst_sel:DWORD dst_unused:UNUSED_PAD src0_sel:DWORD src1_sel:BYTE_0
	v_and_b32_e32 v3, 32, v3
	v_bfe_i32 v4, v4, 0, 16
	v_lshlrev_b32_e32 v8, 1, v6
	v_lshrrev_b32_e32 v9, 2, v6
	v_and_b32_e32 v10, 3, v2
	s_mov_b32 s5, 0xfffe0
	v_add_u32_e32 v7, v3, v4
	v_and_b32_e32 v8, 24, v8
	v_and_b32_e32 v9, 4, v9
	v_and_or_b32 v10, v6, s5, v10
	v_mul_lo_u32 v6, v6, s60
	v_or3_b32 v8, v10, v9, v8
	v_add_lshl_u32 v164, v7, v6, 1
	v_lshlrev_b32_e32 v6, 1, v7
	v_lshl_add_u32 v166, v8, 12, v6
	v_add_u32_e32 v6, 0x2000, v5
	v_ashrrev_i32_e32 v5, 31, v6
	v_lshrrev_b32_e32 v5, 22, v5
	v_add_u32_e32 v5, v6, v5
	v_ashrrev_i32_e32 v5, 10, v5
	v_mul_i32_i24_e32 v7, 0x400, v5
	v_sub_u32_e32 v6, v6, v7
	v_lshrrev_b32_e32 v7, 4, v6
	v_bitop3_b32 v8, v7, v6, 32 bitop3:0x6c
	v_lshlrev_b32_e32 v6, 3, v5
	v_and_b32_e32 v7, -16, v6
	v_ashrrev_i32_e32 v6, 31, v8
	v_lshrrev_b32_e32 v6, 26, v6
	v_add_u32_e32 v9, v8, v6
	v_ashrrev_i32_e32 v6, 6, v9
	v_and_b32_e32 v9, 0xc0, v9
	v_add_u32_e32 v10, v6, v7
	v_sub_u32_e32 v8, v8, v9
	v_and_b32_e32 v13, 3, v6
	v_lshlrev_b32_e32 v7, 5, v5
	v_ashrrev_i16_sdwa v8, v237, sext(v8) dst_sel:DWORD dst_unused:UNUSED_PAD src0_sel:DWORD src1_sel:BYTE_0
	v_and_or_b32 v13, v10, s5, v13
	s_ashr_i32 s5, s35, 6
	v_and_b32_e32 v7, 32, v7
	v_bfe_i32 v8, v8, 0, 16
	v_lshlrev_b32_e32 v11, 1, v10
	v_lshrrev_b32_e32 v12, 2, v10
	s_lshl_b32 s42, s5, 10
	v_add_u32_e32 v9, v7, v8
	v_and_b32_e32 v11, 24, v11
	v_and_b32_e32 v12, 4, v12
	v_mul_lo_u32 v10, v10, s60
	s_add_i32 s43, s42, 0
	v_or3_b32 v11, v13, v12, v11
	v_add_lshl_u32 v168, v9, v10, 1
	v_lshlrev_b32_e32 v9, 1, v9
	s_add_i32 m0, s43, 0x10000
	v_lshl_add_u32 v170, v11, 12, v9
	global_load_lds_dwordx4 v166, s[12:13]
	s_add_i32 m0, s43, 0x12000
	s_ashr_i32 s4, s35, 8
	global_load_lds_dwordx4 v170, s[12:13]
	s_mov_b32 m0, s43
	s_add_i32 s44, s43, 0x2000
	global_load_lds_dwordx4 v164, s[10:11]
	s_mov_b32 m0, s44
	s_add_u32 s6, s12, 0x80000
	global_load_lds_dwordx4 v168, s[10:11]
	s_addc_u32 s7, s13, 0
	s_add_i32 m0, s43, 0x14000
	v_mov_b64_e32 v[184:185], 0x33f
	global_load_lds_dwordx4 v166, s[6:7]
	s_add_i32 m0, s43, 0x16000
	s_nop 0
	global_load_lds_dwordx4 v170, s[6:7]
	s_add_u32 s6, s10, 0x1c0000
	s_addc_u32 s7, s11, 0
	s_add_i32 s45, s43, 0x4000
	s_mov_b32 m0, s45
	s_add_i32 s46, s43, 0x6000
	global_load_lds_dwordx4 v164, s[6:7]
	s_mov_b32 m0, s46
	s_cmp_lg_u32 s4, 1
	global_load_lds_dwordx4 v168, s[6:7]
	s_cbranch_scc1 .LBB0_1162
	s_barrier

.LBB0_1306:
	v_readlane_b32 s50, v255, 1
	v_mov_b64_e32 v[184:185], 0x700
	s_barrier
